# GQA: only the 128 second-round units are split into KV halves (static roles: half0 publishes f32 partial, half1 combines); first 256 units unchanged
# speedup vs baseline: 1.0100x; 1.0100x over previous
; __device__ __forceinline__ int opaque_tid() { int t; asm volatile("v_mov_b32 %0, %1" : "=v"(t) : "v"((int)threadIdx.x)); return t; }
; __global__ void __launch_bounds__(NTHREADS, 2) mega_fwd(Params P) {
;     ...
;                 if (opaque_tid() == 0) qslot[0] = (int)atomicAdd(ctl + 64 * (l + 1), 1u);
;                 __syncthreads();
;                 const int idx = __builtin_amdgcn_readfirstlane(qslot[0]);
;                 __syncthreads();
;                 if (idx >= ntot) break;
;                 if (idx < n_gqa) {
;                     const int qb = idx / 12, r12 = idx % 12, b = r12 / 6, h = r12 % 6; const size_t rb = (size_t)b * RPB;
;                     ap::unit<8, 0>(qkv + (rb + 256 * qb) * DIN + C_QC + 64 * h, qkv + rb * DIN + C_KC + 64 * (h / 3), qkv + rb * DIN + C_VC + 64 * (h / 3),
;                                    omix + (rb + 256 * qb) * DM + 640 + 64 * h, ssb + (rb + 256 * qb) * 4 + 2, 132, (char*)lds, 0, 0, tcos[4096 + l]);
.LBB0_443:
	s_or_b64 exec, exec, s[0:1]
	v_readlane_b32 s0, v254, 42
	s_waitcnt lgkmcnt(0)
	s_barrier
	v_mov_b32_e32 v0, s0
	ds_read_b32 v0, v0
	s_mov_b64 s[0:1], -1
	s_waitcnt lgkmcnt(0)
	s_barrier
	v_readfirstlane_b32 s48, v0
	s_nop 0
	s_mov_b32 s101, 2
	s_cmpk_lt_u32 s48, 0x100
	s_cbranch_scc1 .Lq_done
	s_cmpk_lt_u32 s48, 0x200
	s_cbranch_scc0 .Lq_other
	s_sub_i32 s48, s48, 0x100
	s_and_b32 s101, s48, 1
	s_lshr_b32 s48, s48, 1
	s_add_i32 s48, s48, 0x100
	s_branch .Lq_done
.Lq_other:
	s_sub_i32 s48, s48, 0x80

; __device__ __forceinline__ int opaque_tid() { int t; asm volatile("v_mov_b32 %0, %1" : "=v"(t) : "v"((int)threadIdx.x)); return t; }
; #define WAIT_BAR(N) asm volatile("s_waitcnt vmcnt(" #N ") lgkmcnt(0)\n\ts_barrier" ::: "memory")
; #define DMA_K(t, slot) glds16s(kvo, Kh + (long)TROW(t) * PITCH, (unsigned)__builtin_amdgcn_readfirstlane(kdst + (slot)))
;     const int tid = opaque_tid(), lane = tid & 63, r32 = lane & 31, hi = lane >> 5; const int wid = __builtin_amdgcn_readfirstlane(tid >> 6);
;     const bf16_t* Qw = Q + (long)(wid * QBLK) * PITCH;
;     const unsigned lds0 = (unsigned)(uintptr_t)shm;
;     float* wsf = (float*)(shm + LDS_WS) + wid * 64;
;     const unsigned kvo = (unsigned)((lane * PITCH + wid * 8) * 2);
;     const unsigned vvo = (unsigned)(((16 * (wid & 3) + (lane >> 2)) * PITCH + (wid >> 2) * 32 + (lane & 3) * 8) * 2);
;     const unsigned kdst = lds0 + LDS_K + wid * 1024, vdst = lds0 + LDS_V + wid * 1024;
;     ...
;     const char* Kbase = shm + LDS_K; bf16x8 kf[8];
;     const lds_cptr shm3 = (lds_cptr)shm; const lds_cptr kp0 = shm3 + LDS_K + hi * 1024 + r32 * 16; const lds_cptr vp0 = shm3 + LDS_V + ((lane >> 4) & 1) * 32 + (lane & 3) * 8 + (4 * hi + ((lane & 15) >> 2)) * 64;
;     DMA_K(0, 0); DMA_V(0, 0); DMA_K(1, SLOTB);
;     bf16x8 qr[4];
; #pragma unroll
;     for (int d0 = 0; d0 < 4; ++d0) qr[d0] = *reinterpret_cast<const bf16x8*>(&Qw[(long)r32 * PITCH + d0 * 16 + hi * 8]);
;     float mhat = (MODE == 0) ? bref : 0.f, l_reg = 0.f; f32x16 o[2]; o[0] = f32x16{}; o[1] = f32x16{}; f32x16 negm = f32x16{};
;     if (MODE == 0) { _Pragma("unroll") for (int r = 0; r < 16; ++r) negm[r] = -bref; }
;     if (MODE != 1) asm volatile("" : "+v"(negm));
;     int na_gr = 0, na_rs = 0, na_qc = 0, na_cs = 0;
;     if (MODE == 1) { na_gr = r0 + (wid >> 1); na_rs = min(max(na_gr - 4, 0), 120); na_qc = 32 * (wid & 1) + r32; na_cs = min(max(na_qc - 8, 0), 48); }
;     ...
;     bool resc = false;
;     ...
;     f32x16 pA0, pA1, pB0, pB1;
;     int sl_prev = 0, sl_cur = 0, sl_next = SLOTB;
;     ...
;     DMA_K(2, 2 * SLOTB);
;     WAIT_BAR(3);
;     qkt(pA0, pA1, Kbase, qr, negm, r32, hi); asm volatile("s_nop 15\n\ts_nop 7" : "+v"(pA0), "+v"(pA1));
;     START(pA0, pA1);
;     _Pragma("unroll") for (int r = 0; r < 16; ++r) pA1[r] = __builtin_amdgcn_exp2f(pA1[r]);
;     WAIT_BAR(0);
.LBB0_874:
	s_andn2_b64 vcc, exec, s[0:1]
	s_cbranch_vccnz .LBB0_439
	s_mul_hi_i32 s0, s48, 0x2aaaaaab
	s_lshr_b32 s1, s0, 31
	s_ashr_i32 s3, s0, 1
	s_add_i32 s3, s3, s1
	s_mul_i32 s0, s3, 12
	s_sub_i32 s0, s48, s0
	s_mul_i32 s1, s0, 43
	s_bfe_u32 s2, s1, 0x1000f
	s_bfe_u32 s1, s1, 0x80008
	s_add_i32 s1, s1, s2
	s_sext_i32_i8 s18, s1
	s_mul_i32 s1, s1, 6
	s_mul_i32 s9, s18, 0x2100
	s_lshl_b32 s4, s3, 8
	s_sub_i32 s8, s0, s1
	s_ashr_i32 s5, s9, 31
	s_ashr_i32 s6, s4, 31
	s_add_u32 s4, s9, s4
	s_addc_u32 s5, s5, s6
	s_mul_i32 s6, s5, 0x1200
	s_mul_hi_u32 s7, s4, 0x1200
	s_mov_b64 s[0:1], s[76:77]
	s_add_i32 s7, s7, s6
	s_mul_i32 s6, s4, 0x1200
	s_sext_i32_i8 s2, s8
	s_add_u32 s10, s0, s6
	s_addc_u32 s11, s1, s7
	s_lshl_b32 s0, s2, 6
	s_ashr_i32 s1, s0, 31
	s_lshl_b64 s[6:7], s[0:1], 1
	s_add_u32 s26, s10, s6
	s_addc_u32 s27, s11, s7
	s_mov_b64 s[0:1], s[76:77]
	s_mul_i32 s10, s18, 0x2520000
	s_mul_hi_i32 s9, s9, 0x1200
	s_cmp_eq_u32 s101, 2
	s_cselect_b32 s47, 0x7c, 0x3a
	s_cselect_b32 s46, 0, 0x1290000
	s_cmp_eq_u32 s101, 1
	s_cselect_b32 s40, 0x1290000, 0
	s_add_u32 s10, s10, s40
	s_addc_u32 s9, s9, 0
	s_add_u32 s2, s0, s10
	s_addc_u32 s22, s1, s9
	s_bfe_i32 s0, s8, 0x80000
	s_mulk_i32 s0, 0x56
	s_bfe_u32 s1, s0, 0x1000f
	s_bfe_u32 s0, s0, 0x80008
	s_add_i32 s0, s0, s1
	s_sext_i32_i8 s0, s0
	s_lshl_b32 s0, s0, 6
	s_ashr_i32 s1, s0, 31
	s_lshl_b64 s[16:17], s[0:1], 1
	s_add_u32 s30, s2, s16
	s_addc_u32 s34, s22, s17
	s_add_u32 s14, s30, 0xe400300
	s_addc_u32 s15, s34, 0
	s_mov_b64 s[0:1], s[76:77]
	s_add_u32 s23, s0, s10
	s_addc_u32 s24, s1, s9
	s_add_u32 s35, s23, s16
	s_addc_u32 s36, s24, s17
	v_readlane_b32 s20, v252, 9
	s_add_u32 s12, s35, 0xe401100
	s_mov_b64 s[10:11], s[76:77]
	s_mov_b64 s[8:9], s[76:77]
	s_mov_b64 s[0:1], s[76:77]
	v_readlane_b32 s21, v252, 10
	s_addc_u32 s13, s36, 0
	s_lshl_b64 s[20:21], s[20:21], 2
	s_add_u32 s0, s0, s20
	s_addc_u32 s1, s1, s21
	v_mov_b32_e32 v0, s0
	s_mov_b32 s0, 0x184000
	v_mov_b32_e32 v3, s1
	v_add_co_u32_e32 v2, vcc, s0, v0
	v_mov_b32_e32 v194, 0
	s_nop 0
	v_addc_co_u32_e32 v3, vcc, 0, v3, vcc
	flat_load_dword v6, v[2:3]
	v_mov_b32 v14, v214
	s_waitcnt vmcnt(0) lgkmcnt(0)
	v_xor_b32_e32 v50, 0x80000000, v6
	v_readfirstlane_b32 s25, v14
	s_ashr_i32 s19, s25, 6
	s_lshl_b32 s0, s19, 5
	s_ashr_i32 s1, s0, 31
	s_mul_i32 s20, s19, 0x24000
	s_mul_hi_i32 s21, s0, 0x1200
	s_add_u32 s28, s26, s20
	s_addc_u32 s29, s27, s21
	s_lshl_b32 s20, s19, 4
	v_and_b32_e32 v15, 63, v14
	v_mov_b32_e32 v0, s20
	v_mad_u32_u24 v193, v15, s80, v0
	v_bfe_u32 v0, v14, 2, 4
	v_and_or_b32 v0, s20, 48, v0
	s_ashr_i32 s20, s25, 3
	s_and_b32 s20, s20, 0x7fffffe0
	v_mov_b32_e32 v2, s20
	v_mad_u32_u24 v0, v0, s81, v2
	v_lshlrev_b32_e32 v2, 3, v14
	v_and_b32_e32 v187, 24, v2
	v_and_b32_e32 v17, 31, v14
	v_or_b32_e32 v0, v0, v187
	s_lshl_b32 s21, s19, 10
	v_lshlrev_b32_e32 v192, 1, v0
	s_cmp_lg_u32 0, -1
	v_mul_u32_u24_e32 v0, 0x900, v17
	v_bfe_u32 v186, v14, 5, 1
	s_cselect_b32 s20, 0, 0
	v_lshlrev_b32_e32 v0, 1, v0
	s_add_i32 s26, s21, s20
	v_lshl_or_b32 v0, v186, 4, v0
	s_add_i32 s20, s26, 0x6000
	s_mov_b32 s27, m0
	s_mov_b32 m0, s26
	s_nop 0
	global_load_lds_dwordx4 v193, s[14:15]
	s_mov_b32 m0, s27
	v_lshl_add_u64 v[2:3], s[28:29], 0, v[0:1]
	s_mov_b32 s27, m0
	s_mov_b32 m0, s20
	s_nop 0
	global_load_lds_dwordx4 v192, s[12:13]
	s_mov_b32 m0, s27
	s_sub_u32 s14, s14, s46
	s_subb_u32 s15, s15, 0
	s_sub_u32 s12, s12, s46
	s_subb_u32 s13, s13, 0
	s_add_u32 s38, s30, 0xe448300
	v_add_co_u32_e32 v4, vcc, s82, v2
	s_addc_u32 s39, s34, 0
	s_add_i32 s27, s26, 0x2000
	s_mov_b32 s31, m0
	s_mov_b32 m0, s27
	s_nop 0
	global_load_lds_dwordx4 v193, s[38:39]
	s_mov_b32 m0, s31
	v_addc_co_u32_e32 v5, vcc, 0, v3, vcc
	flat_load_dwordx4 v[162:165], v[4:5]
	s_mov_b64 s[28:29], 0xe400000
	v_lshl_add_u64 v[2:3], v[2:3], 0, s[28:29]
	flat_load_dwordx4 v[158:161], v[2:3] offset:32
	flat_load_dwordx4 v[154:157], v[2:3] offset:64
	flat_load_dwordx4 v[150:153], v[2:3] offset:96
	v_mov_b32_e32 v51, v50
	v_mov_b32_e32 v52, v50
	v_mov_b32_e32 v53, v50
	v_mov_b32_e32 v54, v50
	v_mov_b32_e32 v55, v50
	v_mov_b32_e32 v56, v50
	v_mov_b32_e32 v57, v50
	v_mov_b32_e32 v58, v50
	v_mov_b32_e32 v59, v50
	v_mov_b32_e32 v60, v50
	v_mov_b32_e32 v61, v50
	v_mov_b32_e32 v62, v50
	v_mov_b32_e32 v63, v50
	v_mov_b32_e32 v64, v50
	v_mov_b32_e32 v65, v50
	s_add_u32 s28, s30, 0xe490300
	v_lshlrev_b32_e32 v0, 10, v186
	v_lshlrev_b32_e32 v4, 4, v17
	s_addc_u32 s29, s34, 0
	s_add_i32 s27, s26, 0x4000
	s_mov_b32 s31, m0
	s_mov_b32 m0, s27
	s_nop 0
	global_load_lds_dwordx4 v193, s[28:29]
	s_mov_b32 m0, s31
	v_add3_u32 v191, 0, v0, v4
	s_waitcnt vmcnt(3) lgkmcnt(0)
	s_barrier
	ds_read_b128 v[2:5], v191
	ds_read_b128 v[6:9], v191 offset:512
	s_waitcnt vmcnt(0) lgkmcnt(0)
	v_mfma_f32_32x32x16_bf16 v[34:49], v[2:5], v[162:165], v[50:65]
	s_add_u32 s38, s30, 0xe4d8300
	s_addc_u32 s39, s34, 0
	s_add_u32 s34, s35, 0xe449100
	s_addc_u32 s35, s36, 0
	v_lshlrev_b32_e32 v0, 1, v14
	v_and_b32_e32 v188, 32, v0
	v_lshlrev_b32_e32 v0, 8, v186
	v_mfma_f32_32x32x16_bf16 v[18:33], v[6:9], v[162:165], v[50:65]
	ds_read_b128 v[2:5], v191 offset:2048
	ds_read_b128 v[6:9], v191 offset:2560
	s_mov_b32 s31, 0
	s_mov_b32 s27, -1
	s_movk_i32 s29, 0x2000
	s_movk_i32 s28, 0x4000
	s_waitcnt lgkmcnt(1)
	v_mfma_f32_32x32x16_bf16 v[34:49], v[2:5], v[158:161], v[34:49]
	s_waitcnt lgkmcnt(0)
	v_mfma_f32_32x32x16_bf16 v[18:33], v[6:9], v[158:161], v[18:33]
	ds_read_b128 v[2:5], v191 offset:4096
	ds_read_b128 v[6:9], v191 offset:4608
	s_waitcnt lgkmcnt(1)
	v_mfma_f32_32x32x16_bf16 v[34:49], v[2:5], v[154:157], v[34:49]
	s_waitcnt lgkmcnt(0)
	v_mfma_f32_32x32x16_bf16 v[18:33], v[6:9], v[154:157], v[18:33]
	ds_read_b128 v[2:5], v191 offset:6144
	ds_read_b128 v[6:9], v191 offset:6656
	s_waitcnt lgkmcnt(1)
	v_mfma_f32_32x32x16_bf16 v[34:49], v[2:5], v[150:153], v[34:49]
	v_lshlrev_b32_e32 v3, 4, v14
	v_add_u32_e32 v2, 0, v188
	v_and_or_b32 v189, v3, s83, v0
	v_add3_u32 v190, v2, v187, v189
	s_waitcnt lgkmcnt(0)
	v_mfma_f32_32x32x16_bf16 v[18:33], v[6:9], v[150:153], v[18:33]
	s_nop 15
	s_nop 7
	s_waitcnt vmcnt(0) lgkmcnt(0)
	s_barrier
; #define WAIT_BAR(N) asm volatile("s_waitcnt vmcnt(" #N ") lgkmcnt(0)\n\ts_barrier" ::: "memory")
; #define DMA_K(t, slot) glds16s(kvo, Kh + (long)TROW(t) * PITCH, (unsigned)__builtin_amdgcn_readfirstlane(kdst + (slot)))
; #define DMA_V(t, slot) glds16s(vvo, Vh + (long)TROW(t) * PITCH, (unsigned)__builtin_amdgcn_readfirstlane(vdst + (slot)))
; #define ROT() do { sl_prev = sl_cur; sl_cur = sl_next; sl_next = (sl_next == (NSLOT - 1) * SLOTB) ? 0 : sl_next + SLOTB; } while (0)
;     ...
;     DMA_K(2, 2 * SLOTB);
;     WAIT_BAR(3);
;     qkt(pA0, pA1, Kbase, qr, negm, r32, hi); asm volatile("s_nop 15\n\ts_nop 7" : "+v"(pA0), "+v"(pA1));
;     START(pA0, pA1);
;     _Pragma("unroll") for (int r = 0; r < 16; ++r) pA1[r] = __builtin_amdgcn_exp2f(pA1[r]);
;     WAIT_BAR(0);
;     DMA_K(3, 0); DMA_V(1, SLOTB);
;     ROT();
;     kload8(kf, kp0 + sl_cur);
	s_mov_b32 s30, m0
	s_mov_b32 m0, s26
	s_nop 0
	global_load_lds_dwordx4 v193, s[38:39]
	s_mov_b32 m0, s30
	s_add_i32 s30, s26, 0x8000
	s_mov_b32 s36, m0
	s_mov_b32 m0, s30
	s_nop 0
	global_load_lds_dwordx4 v192, s[34:35]
	s_mov_b32 m0, s36
	ds_read_b128 v[98:101], v191 offset:8192
	ds_read_b128 v[170:173], v191 offset:8704
	ds_read_b128 v[174:177], v191 offset:10240
	ds_read_b128 v[166:169], v191 offset:10752
	ds_read_b128 v[142:145], v191 offset:12288
	ds_read_b128 v[138:141], v191 offset:12800
	ds_read_b128 v[134:137], v191 offset:14336
	ds_read_b128 v[130:133], v191 offset:14848
	v_exp_f32_e32 v82, v34
	v_exp_f32_e32 v83, v35
	v_exp_f32_e32 v84, v36
	v_exp_f32_e32 v85, v37
	v_exp_f32_e32 v86, v38
	v_exp_f32_e32 v87, v39
	v_exp_f32_e32 v88, v40
	v_exp_f32_e32 v89, v41
	v_exp_f32_e32 v90, v42
	v_exp_f32_e32 v91, v43
	v_exp_f32_e32 v92, v44
	v_exp_f32_e32 v93, v45
	v_exp_f32_e32 v94, v46
	v_exp_f32_e32 v95, v47
	v_exp_f32_e32 v96, v48
	v_exp_f32_e32 v97, v49
	v_exp_f32_e32 v66, v18
	v_exp_f32_e32 v67, v19
	v_exp_f32_e32 v68, v20
	v_exp_f32_e32 v69, v21
	v_exp_f32_e32 v70, v22
	v_exp_f32_e32 v71, v23
	v_exp_f32_e32 v72, v24
	v_exp_f32_e32 v73, v25
	v_exp_f32_e32 v74, v26
	v_exp_f32_e32 v75, v27
	v_exp_f32_e32 v76, v28
	v_exp_f32_e32 v77, v29
	v_exp_f32_e32 v78, v30
	v_exp_f32_e32 v79, v31
	v_exp_f32_e32 v80, v32
	v_exp_f32_e32 v81, v33
	s_waitcnt vmcnt(2) lgkmcnt(0)
	s_barrier
	v_mov_b32_e32 v18, 0
	v_mov_b32_e32 v19, v194
	v_mov_b32_e32 v20, v194
	v_mov_b32_e32 v21, v194
	v_mov_b32_e32 v22, v194
	v_mov_b32_e32 v23, v194
	v_mov_b32_e32 v24, v194
	v_mov_b32_e32 v25, v194
	v_mov_b32_e32 v26, v194
	v_mov_b32_e32 v27, v194
	v_mov_b32_e32 v28, v194
	v_mov_b32_e32 v29, v194
	v_mov_b32_e32 v30, v194
	v_mov_b32_e32 v31, v194
	v_mov_b32_e32 v32, v194
	v_mov_b32_e32 v33, v194
	v_mov_b32_e32 v34, 0
	v_mov_b32_e32 v35, v194
	v_mov_b32_e32 v36, v194
	v_mov_b32_e32 v37, v194
	v_mov_b32_e32 v38, v194
	v_mov_b32_e32 v39, v194
	v_mov_b32_e32 v40, v194
	v_mov_b32_e32 v41, v194
	v_mov_b32_e32 v42, v194
	v_mov_b32_e32 v43, v194
	v_mov_b32_e32 v44, v194
	v_mov_b32_e32 v45, v194
	v_mov_b32_e32 v46, v194
	v_mov_b32_e32 v47, v194
	v_mov_b32_e32 v48, v194
	v_mov_b32_e32 v49, v194
.LBB0_876:
	v_add_u32_e32 v195, s31, v190
	ds_read_b64_tr_b16 v[182:183], v195 offset:24576
	ds_read_b64_tr_b16 v[184:185], v195 offset:25088
	v_add_f32_e32 v2, v82, v83
	v_add_f32_e32 v2, v84, v2
	v_add_f32_e32 v2, v85, v2
	v_add_f32_e32 v2, v86, v2
	v_add_f32_e32 v2, v87, v2
	v_cvt_pk_bf16_f32 v146, v82, v83
	v_cvt_pk_bf16_f32 v147, v84, v85
	s_waitcnt lgkmcnt(9)
	v_mfma_f32_32x32x16_bf16 v[114:129], v[98:101], v[162:165], v[50:65]
	ds_read_b64_tr_b16 v[178:179], v195 offset:28672
	ds_read_b64_tr_b16 v[180:181], v195 offset:29184
	s_waitcnt lgkmcnt(10)
	v_mfma_f32_32x32x16_bf16 v[98:113], v[170:173], v[162:165], v[50:65]
	v_add_f32_e32 v2, v88, v2
	v_add_f32_e32 v2, v89, v2
	v_add_f32_e32 v2, v90, v2
	v_add_f32_e32 v2, v91, v2
	v_cvt_pk_bf16_f32 v148, v86, v87
	v_cvt_pk_bf16_f32 v149, v88, v89
	ds_read_b64_tr_b16 v[82:83], v195 offset:25600
	ds_read_b64_tr_b16 v[84:85], v195 offset:26112
	v_add_f32_e32 v2, v92, v2
	v_add_f32_e32 v2, v93, v2
	v_add_f32_e32 v2, v94, v2
	v_add_f32_e32 v2, v95, v2
	v_cvt_pk_bf16_f32 v10, v90, v91
	v_cvt_pk_bf16_f32 v11, v92, v93
	s_waitcnt lgkmcnt(11)
	v_mfma_f32_32x32x16_bf16 v[114:129], v[174:177], v[158:161], v[114:129]
	ds_read_b64_tr_b16 v[86:87], v195 offset:29696
	ds_read_b64_tr_b16 v[88:89], v195 offset:30208
	s_waitcnt lgkmcnt(12)
	v_mfma_f32_32x32x16_bf16 v[98:113], v[166:169], v[158:161], v[98:113]
	v_add_f32_e32 v2, v96, v2
	v_add_f32_e32 v2, v97, v2
	v_add_f32_e32 v2, v66, v2
	v_add_f32_e32 v2, v67, v2
	v_cvt_pk_bf16_f32 v12, v94, v95
	v_cvt_pk_bf16_f32 v13, v96, v97
	ds_read_b64_tr_b16 v[90:91], v195 offset:26624
	ds_read_b64_tr_b16 v[92:93], v195 offset:27136
	v_add_f32_e32 v2, v68, v2
	v_add_f32_e32 v2, v69, v2
	v_add_f32_e32 v2, v70, v2
	v_add_f32_e32 v2, v71, v2
	v_cvt_pk_bf16_f32 v6, v66, v67
	v_cvt_pk_bf16_f32 v7, v68, v69
	s_waitcnt lgkmcnt(13)
	v_mfma_f32_32x32x16_bf16 v[114:129], v[142:145], v[154:157], v[114:129]
	ds_read_b64_tr_b16 v[66:67], v195 offset:30720
	ds_read_b64_tr_b16 v[68:69], v195 offset:31232
	s_waitcnt lgkmcnt(14)
	v_mfma_f32_32x32x16_bf16 v[98:113], v[138:141], v[154:157], v[98:113]
	v_add_f32_e32 v2, v72, v2
	v_add_f32_e32 v2, v73, v2
	v_add_f32_e32 v2, v74, v2
	v_add_f32_e32 v2, v75, v2
	v_cvt_pk_bf16_f32 v8, v70, v71
	v_cvt_pk_bf16_f32 v9, v72, v73
	ds_read_b64_tr_b16 v[70:71], v195 offset:27648
	ds_read_b64_tr_b16 v[72:73], v195 offset:28160
	v_add_f32_e32 v2, v76, v2
	v_add_f32_e32 v2, v77, v2
	v_add_f32_e32 v2, v78, v2
	v_add_f32_e32 v94, v79, v2
	v_cvt_pk_bf16_f32 v2, v74, v75
	v_cvt_pk_bf16_f32 v3, v76, v77
	s_waitcnt lgkmcnt(14)
	v_mfma_f32_32x32x16_bf16 v[114:129], v[134:137], v[150:153], v[114:129]
	ds_read_b64_tr_b16 v[74:75], v195 offset:31744
	ds_read_b64_tr_b16 v[76:77], v195 offset:32256
	v_mfma_f32_32x32x16_bf16 v[98:113], v[130:133], v[150:153], v[98:113]
	v_add_f32_e32 v4, v80, v94
	v_add_f32_e32 v4, v81, v4
	v_add_f32_e32 v195, 0, v4
	v_cvt_pk_bf16_f32 v4, v78, v79
	v_cvt_pk_bf16_f32 v5, v80, v81
	s_add_u32 s31, s2, s16
	s_addc_u32 s34, s22, s17
	s_add_u32 s36, s31, 0xe520300
	s_addc_u32 s37, s34, 0
	s_add_i32 s30, s29, s26
	s_mov_b32 s35, m0
	s_mov_b32 m0, s30
	s_nop 0
	global_load_lds_dwordx4 v193, s[36:37]
	s_mov_b32 m0, s35
	s_add_u32 s35, s23, s16
	s_addc_u32 s36, s24, s17
	s_add_u32 s38, s35, 0xe491100
	s_addc_u32 s39, s36, 0
	s_add_i32 s30, s28, s20
	s_mov_b32 s37, m0
	s_mov_b32 m0, s30
	s_nop 0
	global_load_lds_dwordx4 v192, s[38:39]
	s_mov_b32 m0, s37
	s_waitcnt lgkmcnt(14)
	v_mfma_f32_32x32x16_bf16 v[18:33], v[146:149], v[182:185], v[18:33]
	v_exp_f32_e32 v114, v114
	v_exp_f32_e32 v115, v115
	v_exp_f32_e32 v116, v116
	v_exp_f32_e32 v117, v117
	s_waitcnt lgkmcnt(12)
	v_mfma_f32_32x32x16_bf16 v[34:49], v[146:149], v[178:181], v[34:49]
	v_exp_f32_e32 v118, v118
	v_exp_f32_e32 v119, v119
	v_exp_f32_e32 v120, v120
	v_exp_f32_e32 v121, v121
	v_add_u32_e32 v94, s28, v191
	ds_read_b128 v[78:81], v94
	ds_read_b128 v[134:137], v94 offset:512
	s_waitcnt lgkmcnt(12)
	v_mfma_f32_32x32x16_bf16 v[18:33], v[10:13], v[82:85], v[18:33]
	v_exp_f32_e32 v122, v122
	v_exp_f32_e32 v123, v123
	v_exp_f32_e32 v124, v124
	v_exp_f32_e32 v125, v125
	ds_read_b128 v[138:141], v94 offset:2048
	ds_read_b128 v[142:145], v94 offset:2560
	s_waitcnt lgkmcnt(12)
	v_mfma_f32_32x32x16_bf16 v[34:49], v[10:13], v[86:89], v[34:49]
	v_exp_f32_e32 v126, v126
	v_exp_f32_e32 v127, v127
	v_exp_f32_e32 v128, v128
	v_exp_f32_e32 v129, v129
	ds_read_b128 v[166:169], v94 offset:4096
	ds_read_b128 v[170:173], v94 offset:4608
	s_waitcnt lgkmcnt(12)
	v_mfma_f32_32x32x16_bf16 v[18:33], v[6:9], v[90:93], v[18:33]
	v_exp_f32_e32 v98, v98
	v_exp_f32_e32 v99, v99
	v_exp_f32_e32 v100, v100
	v_exp_f32_e32 v101, v101
	ds_read_b128 v[174:177], v94 offset:6144
	ds_read_b128 v[130:133], v94 offset:6656
	s_waitcnt lgkmcnt(12)
	v_mfma_f32_32x32x16_bf16 v[34:49], v[6:9], v[66:69], v[34:49]
	v_exp_f32_e32 v102, v102
	v_exp_f32_e32 v103, v103
	v_exp_f32_e32 v104, v104
	v_exp_f32_e32 v105, v105
	s_waitcnt lgkmcnt(10)
	v_mfma_f32_32x32x16_bf16 v[18:33], v[2:5], v[70:73], v[18:33]
	v_exp_f32_e32 v106, v106
	v_exp_f32_e32 v107, v107
	v_exp_f32_e32 v108, v108
	v_exp_f32_e32 v109, v109
	s_waitcnt lgkmcnt(8)
	v_mfma_f32_32x32x16_bf16 v[34:49], v[2:5], v[74:77], v[34:49]
	v_exp_f32_e32 v110, v110
	v_exp_f32_e32 v111, v111
	v_exp_f32_e32 v112, v112
	v_exp_f32_e32 v113, v113
	s_waitcnt vmcnt(2) lgkmcnt(0)
	s_barrier
	s_add_i32 s30, s28, 0x2000
	s_cmpk_lg_i32 s28, 0x4000
	s_cselect_b32 s30, s30, 0
	v_add_u32_e32 v196, s29, v190
	ds_read_b64_tr_b16 v[178:179], v196 offset:24576
	ds_read_b64_tr_b16 v[180:181], v196 offset:25088
	s_waitcnt lgkmcnt(9)
	v_mfma_f32_32x32x16_bf16 v[82:97], v[78:81], v[162:165], v[50:65]
	v_add_f32_e32 v2, v114, v115
	v_add_f32_e32 v2, v116, v2
	v_add_f32_e32 v2, v117, v2
	v_add_f32_e32 v2, v118, v2
	v_add_f32_e32 v2, v119, v2
	v_cvt_pk_bf16_f32 v146, v114, v115
	v_cvt_pk_bf16_f32 v147, v116, v117
	ds_read_b64_tr_b16 v[182:183], v196 offset:28672
	ds_read_b64_tr_b16 v[184:185], v196 offset:29184
	s_waitcnt lgkmcnt(10)
	v_mfma_f32_32x32x16_bf16 v[66:81], v[134:137], v[162:165], v[50:65]
	v_add_f32_e32 v2, v120, v2
	v_add_f32_e32 v2, v121, v2
	v_add_f32_e32 v2, v122, v2
	v_add_f32_e32 v2, v123, v2
	v_cvt_pk_bf16_f32 v148, v118, v119
	v_cvt_pk_bf16_f32 v149, v120, v121
	ds_read_b64_tr_b16 v[114:115], v196 offset:25600
	ds_read_b64_tr_b16 v[116:117], v196 offset:26112
	s_waitcnt lgkmcnt(11)
	v_mfma_f32_32x32x16_bf16 v[82:97], v[138:141], v[158:161], v[82:97]
	v_add_f32_e32 v2, v124, v2
	v_add_f32_e32 v2, v125, v2
	v_add_f32_e32 v2, v126, v2
	v_add_f32_e32 v2, v127, v2
	v_cvt_pk_bf16_f32 v10, v122, v123
	v_cvt_pk_bf16_f32 v11, v124, v125
	ds_read_b64_tr_b16 v[118:119], v196 offset:29696
	ds_read_b64_tr_b16 v[120:121], v196 offset:30208
	s_waitcnt lgkmcnt(12)
	v_mfma_f32_32x32x16_bf16 v[66:81], v[142:145], v[158:161], v[66:81]
	v_add_f32_e32 v2, v128, v2
	v_add_f32_e32 v2, v129, v2
	v_add_f32_e32 v2, v98, v2
	v_add_f32_e32 v2, v99, v2
	v_cvt_pk_bf16_f32 v12, v126, v127
	v_cvt_pk_bf16_f32 v13, v128, v129
	ds_read_b64_tr_b16 v[122:123], v196 offset:26624
	ds_read_b64_tr_b16 v[124:125], v196 offset:27136
	s_waitcnt lgkmcnt(13)
	v_mfma_f32_32x32x16_bf16 v[82:97], v[166:169], v[154:157], v[82:97]
	v_add_f32_e32 v2, v100, v2
	v_add_f32_e32 v2, v101, v2
	v_add_f32_e32 v2, v102, v2
	v_add_f32_e32 v2, v103, v2
	v_cvt_pk_bf16_f32 v6, v98, v99
	v_cvt_pk_bf16_f32 v7, v100, v101
	ds_read_b64_tr_b16 v[126:127], v196 offset:30720
	ds_read_b64_tr_b16 v[128:129], v196 offset:31232
	s_waitcnt lgkmcnt(14)
	v_mfma_f32_32x32x16_bf16 v[66:81], v[170:173], v[154:157], v[66:81]
	v_add_f32_e32 v2, v104, v2
	v_add_f32_e32 v2, v105, v2
	v_add_f32_e32 v2, v106, v2
	v_add_f32_e32 v2, v107, v2
	v_cvt_pk_bf16_f32 v8, v102, v103
	v_cvt_pk_bf16_f32 v9, v104, v105
	ds_read_b64_tr_b16 v[102:103], v196 offset:27648
	ds_read_b64_tr_b16 v[104:105], v196 offset:28160
	s_waitcnt lgkmcnt(14)
	v_mfma_f32_32x32x16_bf16 v[82:97], v[174:177], v[150:153], v[82:97]
	v_add_f32_e32 v2, v108, v2
	v_add_f32_e32 v2, v109, v2
	v_add_f32_e32 v2, v110, v2
	v_add_f32_e32 v98, v111, v2
	v_cvt_pk_bf16_f32 v2, v106, v107
	v_cvt_pk_bf16_f32 v3, v108, v109
	ds_read_b64_tr_b16 v[106:107], v196 offset:31744
	ds_read_b64_tr_b16 v[108:109], v196 offset:32256
	v_mfma_f32_32x32x16_bf16 v[66:81], v[130:133], v[150:153], v[66:81]
	v_add_f32_e32 v4, v112, v98
	v_add_f32_e32 v4, v113, v4
	v_add_f32_e32 v196, 0, v4
	v_cvt_pk_bf16_f32 v4, v110, v111
	v_cvt_pk_bf16_f32 v5, v112, v113
	s_add_u32 s38, s31, 0xe568300
	s_addc_u32 s39, s34, 0
	s_add_i32 s29, s28, s26
	s_mov_b32 s31, m0
	s_mov_b32 m0, s29
	s_nop 0
	global_load_lds_dwordx4 v193, s[38:39]
	s_mov_b32 m0, s31
	s_add_u32 s34, s35, 0xe4d9100
	s_addc_u32 s35, s36, 0
	s_add_i32 s29, s30, s20
	s_mov_b32 s31, m0
	s_mov_b32 m0, s29
	s_nop 0
	global_load_lds_dwordx4 v192, s[34:35]
	s_mov_b32 m0, s31
	s_waitcnt lgkmcnt(14)
	v_mfma_f32_32x32x16_bf16 v[18:33], v[146:149], v[178:181], v[18:33]
	v_exp_f32_e32 v82, v82
	v_exp_f32_e32 v83, v83
	v_exp_f32_e32 v84, v84
	v_exp_f32_e32 v85, v85
	s_waitcnt lgkmcnt(12)
; #define WAIT_BAR(N) asm volatile("s_waitcnt vmcnt(" #N ") lgkmcnt(0)\n\ts_barrier" ::: "memory")
; #define RESC() do { if (resc) { asm volatile("s_waitcnt lgkmcnt(0)" ::: "memory"); \
;       _Pragma("unroll") for (int d_ = 0; d_ < 2; ++d_) _Pragma("unroll") for (int r = 0; r < 16; ++r) o[d_][r] *= wsf[crow(r, hi)]; } } while (0)
; #define ROT() do { sl_prev = sl_cur; sl_cur = sl_next; sl_next = (sl_next == (NSLOT - 1) * SLOTB) ? 0 : sl_next + SLOTB; } while (0)
; #define ENDW(tt) do { if ((tt) + 3 < NT) { WAIT_BAR(2); } else if ((tt) + 2 < NT) { WAIT_BAR(1); } else { WAIT_BAR(0); } } while (0)
;     ...
;     int t = 1;
;     for (; t + 5 < NT; t += 2) {
;         STEP(pB0, pB1, pA0, pA1, t, true, true, true);     WAIT_BAR(2); RESC(); ROT();
;         STEP(pA0, pA1, pB0, pB1, t + 1, true, true, true); WAIT_BAR(2); RESC(); ROT();
;     }
;     ...
;     for (; t + 1 < NT; t += 2) {
;         STEP(pB0, pB1, pA0, pA1, t, (t + 3 < NT), (t + 1 < NT), (t + 1 < NT));         ENDW(t);     RESC(); ROT();
;         STEP(pA0, pA1, pB0, pB1, t + 1, (t + 4 < NT), (t + 2 < NT), (t + 2 < NT));     ENDW(t + 1); RESC(); ROT();
;     }
	v_mfma_f32_32x32x16_bf16 v[34:49], v[146:149], v[182:185], v[34:49]
	v_exp_f32_e32 v86, v86
	v_exp_f32_e32 v87, v87
	v_exp_f32_e32 v88, v88
	v_exp_f32_e32 v89, v89
	v_add_u32_e32 v110, s30, v191
	ds_read_b128 v[98:101], v110
	ds_read_b128 v[170:173], v110 offset:512
	s_waitcnt lgkmcnt(12)
	v_mfma_f32_32x32x16_bf16 v[18:33], v[10:13], v[114:117], v[18:33]
	v_exp_f32_e32 v90, v90
	v_exp_f32_e32 v91, v91
	v_exp_f32_e32 v92, v92
	v_exp_f32_e32 v93, v93
	ds_read_b128 v[174:177], v110 offset:2048
	ds_read_b128 v[166:169], v110 offset:2560
	s_waitcnt lgkmcnt(12)
	v_mfma_f32_32x32x16_bf16 v[34:49], v[10:13], v[118:121], v[34:49]
	v_exp_f32_e32 v94, v94
	v_exp_f32_e32 v95, v95
	v_exp_f32_e32 v96, v96
	v_exp_f32_e32 v97, v97
	ds_read_b128 v[142:145], v110 offset:4096
	ds_read_b128 v[138:141], v110 offset:4608
	s_waitcnt lgkmcnt(12)
	v_mfma_f32_32x32x16_bf16 v[18:33], v[6:9], v[122:125], v[18:33]
	v_exp_f32_e32 v66, v66
	v_exp_f32_e32 v67, v67
	v_exp_f32_e32 v68, v68
	v_exp_f32_e32 v69, v69
	ds_read_b128 v[134:137], v110 offset:6144
	ds_read_b128 v[130:133], v110 offset:6656
	s_waitcnt lgkmcnt(12)
	v_mfma_f32_32x32x16_bf16 v[34:49], v[6:9], v[126:129], v[34:49]
	v_exp_f32_e32 v70, v70
	v_exp_f32_e32 v71, v71
	v_exp_f32_e32 v72, v72
	v_exp_f32_e32 v73, v73
	s_waitcnt lgkmcnt(10)
	v_mfma_f32_32x32x16_bf16 v[18:33], v[2:5], v[102:105], v[18:33]
	v_exp_f32_e32 v74, v74
	v_exp_f32_e32 v75, v75
	v_exp_f32_e32 v76, v76
	v_exp_f32_e32 v77, v77
	s_waitcnt lgkmcnt(8)
	v_mfma_f32_32x32x16_bf16 v[34:49], v[2:5], v[106:109], v[34:49]
	v_exp_f32_e32 v78, v78
	v_exp_f32_e32 v79, v79
	v_exp_f32_e32 v80, v80
	v_exp_f32_e32 v81, v81
	s_add_i32 s34, s30, 0x2000
	s_cmpk_lg_i32 s30, 0x4000
	s_mov_b32 s31, s28
	s_cselect_b32 s28, s34, 0
	s_add_i32 s27, s27, 2
	s_add_u32 s23, s23, 0x90000
	s_addc_u32 s24, s24, 0
	s_waitcnt vmcnt(2) lgkmcnt(0)
	s_barrier
	s_add_u32 s2, s2, 0x90000
	v_add_f32_e32 v2, v194, v195
	s_addc_u32 s22, s22, 0
	s_mov_b32 s29, s30
	v_add_f32_e32 v194, v2, v196
	s_cmp_gt_u32 s27, s47
	s_cbranch_scc0 .LBB0_876
	s_and_b32 s2, s25, 0x3fffffc0
	s_lshl_b32 s2, s2, 2
	s_add_i32 s2, s2, 0
	ds_read_b64_tr_b16 v[182:183], v190 offset:24576
	ds_read_b64_tr_b16 v[184:185], v190 offset:25088
	v_add_f32_e32 v2, v82, v83
	v_add_f32_e32 v2, v84, v2
	v_add_f32_e32 v2, v85, v2
	v_add_f32_e32 v2, v86, v2
	v_add_f32_e32 v2, v87, v2
	v_cvt_pk_bf16_f32 v146, v82, v83
	v_cvt_pk_bf16_f32 v147, v84, v85
	s_waitcnt lgkmcnt(9)
	v_mfma_f32_32x32x16_bf16 v[114:129], v[98:101], v[162:165], v[50:65]
	ds_read_b64_tr_b16 v[178:179], v190 offset:28672
	ds_read_b64_tr_b16 v[180:181], v190 offset:29184
	v_add_f32_e32 v2, v88, v2
	v_add_f32_e32 v2, v89, v2
	v_add_f32_e32 v2, v90, v2
	v_add_f32_e32 v2, v91, v2
	v_cvt_pk_bf16_f32 v148, v86, v87
	v_cvt_pk_bf16_f32 v149, v88, v89
	s_waitcnt lgkmcnt(10)
	v_mfma_f32_32x32x16_bf16 v[98:113], v[170:173], v[162:165], v[50:65]
	ds_read_b64_tr_b16 v[82:83], v190 offset:25600
	ds_read_b64_tr_b16 v[84:85], v190 offset:26112
	v_add_f32_e32 v2, v92, v2
	v_add_f32_e32 v2, v93, v2
	v_add_f32_e32 v2, v94, v2
	v_add_f32_e32 v2, v95, v2
	v_cvt_pk_bf16_f32 v10, v90, v91
	v_cvt_pk_bf16_f32 v11, v92, v93
	s_waitcnt lgkmcnt(11)
	v_mfma_f32_32x32x16_bf16 v[114:129], v[174:177], v[158:161], v[114:129]
	ds_read_b64_tr_b16 v[86:87], v190 offset:29696
	ds_read_b64_tr_b16 v[88:89], v190 offset:30208
	v_add_f32_e32 v2, v96, v2
	v_add_f32_e32 v2, v97, v2
	v_add_f32_e32 v2, v66, v2
	v_add_f32_e32 v2, v67, v2
	v_cvt_pk_bf16_f32 v12, v94, v95
	v_cvt_pk_bf16_f32 v13, v96, v97
	s_waitcnt lgkmcnt(12)
	v_mfma_f32_32x32x16_bf16 v[98:113], v[166:169], v[158:161], v[98:113]
	ds_read_b64_tr_b16 v[90:91], v190 offset:26624
	ds_read_b64_tr_b16 v[92:93], v190 offset:27136
	v_add_f32_e32 v2, v68, v2
	v_add_f32_e32 v2, v69, v2
	v_add_f32_e32 v2, v70, v2
	v_add_f32_e32 v2, v71, v2
	v_cvt_pk_bf16_f32 v6, v66, v67
	v_cvt_pk_bf16_f32 v7, v68, v69
	s_waitcnt lgkmcnt(13)
	v_mfma_f32_32x32x16_bf16 v[114:129], v[142:145], v[154:157], v[114:129]
	ds_read_b64_tr_b16 v[66:67], v190 offset:30720
	ds_read_b64_tr_b16 v[68:69], v190 offset:31232
	v_add_f32_e32 v2, v72, v2
	v_add_f32_e32 v2, v73, v2
	v_add_f32_e32 v2, v74, v2
	v_add_f32_e32 v2, v75, v2
	v_cvt_pk_bf16_f32 v8, v70, v71
	v_cvt_pk_bf16_f32 v9, v72, v73
	s_waitcnt lgkmcnt(14)
	v_mfma_f32_32x32x16_bf16 v[98:113], v[138:141], v[154:157], v[98:113]
	ds_read_b64_tr_b16 v[70:71], v190 offset:27648
	ds_read_b64_tr_b16 v[72:73], v190 offset:28160
	v_add_f32_e32 v2, v76, v2
	v_add_f32_e32 v2, v77, v2
	v_add_f32_e32 v2, v78, v2
	v_add_f32_e32 v94, v79, v2
	v_cvt_pk_bf16_f32 v2, v74, v75
	v_cvt_pk_bf16_f32 v3, v76, v77
	s_waitcnt lgkmcnt(14)
	v_mfma_f32_32x32x16_bf16 v[114:129], v[134:137], v[150:153], v[114:129]
	ds_read_b64_tr_b16 v[74:75], v190 offset:31744
	ds_read_b64_tr_b16 v[76:77], v190 offset:32256
	v_add_f32_e32 v4, v80, v94
	v_add_f32_e32 v4, v81, v4
	v_add_f32_e32 v94, 0, v4
	v_cvt_pk_bf16_f32 v4, v78, v79
	v_cvt_pk_bf16_f32 v5, v80, v81
	v_mfma_f32_32x32x16_bf16 v[98:113], v[130:133], v[150:153], v[98:113]
	s_add_u32 s16, s14, 0x2490000
	s_addc_u32 s17, s15, 0
	s_cmp_lg_u32 0, -1
	s_cselect_b32 s23, 0, 0
	s_add_i32 s22, s23, s21
	s_add_i32 s24, s22, 0x2000
	s_mov_b32 s25, m0
	s_mov_b32 m0, s24
	s_nop 0
	global_load_lds_dwordx4 v193, s[16:17]
	s_mov_b32 m0, s25
	s_add_u32 s24, s12, 0x2400000
	s_addc_u32 s25, s13, 0
	s_add_i32 s16, s23, 0xa000
	s_add_i32 s17, s21, s16
	s_mov_b32 s21, m0
	s_mov_b32 m0, s17
	s_nop 0
	global_load_lds_dwordx4 v192, s[24:25]
	s_mov_b32 m0, s21
	v_add_f32_e32 v194, v194, v94
	s_waitcnt lgkmcnt(14)
	v_mfma_f32_32x32x16_bf16 v[18:33], v[146:149], v[182:185], v[18:33]
	v_exp_f32_e32 v114, v114
	v_exp_f32_e32 v115, v115
	v_exp_f32_e32 v116, v116
	v_exp_f32_e32 v117, v117
	s_waitcnt lgkmcnt(12)
	v_mfma_f32_32x32x16_bf16 v[34:49], v[146:149], v[178:181], v[34:49]
	v_exp_f32_e32 v118, v118
	v_exp_f32_e32 v119, v119
	v_exp_f32_e32 v120, v120
	v_exp_f32_e32 v121, v121
	ds_read_b128 v[78:81], v191 offset:16384
	ds_read_b128 v[94:97], v191 offset:16896
	s_waitcnt lgkmcnt(12)
	v_mfma_f32_32x32x16_bf16 v[18:33], v[10:13], v[82:85], v[18:33]
	v_exp_f32_e32 v122, v122
	v_exp_f32_e32 v123, v123
	v_exp_f32_e32 v124, v124
	v_exp_f32_e32 v125, v125
	ds_read_b128 v[166:169], v191 offset:18432
	ds_read_b128 v[170:173], v191 offset:18944
	s_waitcnt lgkmcnt(12)
	v_mfma_f32_32x32x16_bf16 v[34:49], v[10:13], v[86:89], v[34:49]
	v_exp_f32_e32 v126, v126
	v_exp_f32_e32 v127, v127
	v_exp_f32_e32 v128, v128
	v_exp_f32_e32 v129, v129
	ds_read_b128 v[174:177], v191 offset:20480
	ds_read_b128 v[178:181], v191 offset:20992
	s_waitcnt lgkmcnt(12)
	v_mfma_f32_32x32x16_bf16 v[18:33], v[6:9], v[90:93], v[18:33]
	v_exp_f32_e32 v98, v98
	v_exp_f32_e32 v99, v99
	v_exp_f32_e32 v100, v100
	v_exp_f32_e32 v101, v101
	ds_read_b128 v[90:93], v191 offset:22528
	ds_read_b128 v[82:85], v191 offset:23040
	s_waitcnt lgkmcnt(12)
	v_mfma_f32_32x32x16_bf16 v[34:49], v[6:9], v[66:69], v[34:49]
	v_exp_f32_e32 v102, v102
	v_exp_f32_e32 v103, v103
	v_exp_f32_e32 v104, v104
	v_exp_f32_e32 v105, v105
	s_waitcnt lgkmcnt(10)
	v_mfma_f32_32x32x16_bf16 v[18:33], v[2:5], v[70:73], v[18:33]
	v_exp_f32_e32 v106, v106
	v_exp_f32_e32 v107, v107
	v_exp_f32_e32 v108, v108
	v_exp_f32_e32 v109, v109
	s_waitcnt lgkmcnt(8)
	v_mfma_f32_32x32x16_bf16 v[34:49], v[2:5], v[74:77], v[34:49]
	v_exp_f32_e32 v110, v110
	v_exp_f32_e32 v111, v111
	v_exp_f32_e32 v112, v112
	v_exp_f32_e32 v113, v113
	s_waitcnt vmcnt(2) lgkmcnt(0)
	s_barrier
	ds_read_b64_tr_b16 v[182:183], v190 offset:32768
	ds_read_b64_tr_b16 v[184:185], v190 offset:33280
	v_add_f32_e32 v2, v114, v115
	v_add_f32_e32 v2, v116, v2
	v_add_f32_e32 v2, v117, v2
	v_add_f32_e32 v2, v118, v2
	v_add_f32_e32 v2, v119, v2
	v_cvt_pk_bf16_f32 v146, v114, v115
	v_cvt_pk_bf16_f32 v147, v116, v117
	s_waitcnt lgkmcnt(9)
	v_mfma_f32_32x32x16_bf16 v[130:145], v[78:81], v[162:165], v[50:65]
	ds_read_b64_tr_b16 v[114:115], v190 offset:36864
	ds_read_b64_tr_b16 v[116:117], v190 offset:37376
	s_waitcnt lgkmcnt(10)
	v_mfma_f32_32x32x16_bf16 v[66:81], v[94:97], v[162:165], v[50:65]
	v_add_f32_e32 v2, v120, v2
	v_add_f32_e32 v2, v121, v2
	v_add_f32_e32 v2, v122, v2
	v_add_f32_e32 v2, v123, v2
	v_cvt_pk_bf16_f32 v148, v118, v119
	v_cvt_pk_bf16_f32 v149, v120, v121
	ds_read_b64_tr_b16 v[86:87], v190 offset:33792
	ds_read_b64_tr_b16 v[88:89], v190 offset:34304
	v_add_f32_e32 v2, v124, v2
	v_add_f32_e32 v2, v125, v2
	v_add_f32_e32 v2, v126, v2
	v_add_f32_e32 v2, v127, v2
	v_cvt_pk_bf16_f32 v10, v122, v123
	v_cvt_pk_bf16_f32 v11, v124, v125
	s_waitcnt lgkmcnt(11)
	v_mfma_f32_32x32x16_bf16 v[130:145], v[166:169], v[158:161], v[130:145]
	ds_read_b64_tr_b16 v[94:95], v190 offset:37888
	ds_read_b64_tr_b16 v[96:97], v190 offset:38400
	s_waitcnt lgkmcnt(12)
	v_mfma_f32_32x32x16_bf16 v[66:81], v[170:173], v[158:161], v[66:81]
	v_add_f32_e32 v2, v128, v2
	v_add_f32_e32 v2, v129, v2
	v_add_f32_e32 v2, v98, v2
	v_add_f32_e32 v2, v99, v2
	v_cvt_pk_bf16_f32 v12, v126, v127
	v_cvt_pk_bf16_f32 v13, v128, v129
	ds_read_b64_tr_b16 v[118:119], v190 offset:34816
	ds_read_b64_tr_b16 v[120:121], v190 offset:35328
	v_add_f32_e32 v2, v100, v2
	v_add_f32_e32 v2, v101, v2
	v_add_f32_e32 v2, v102, v2
	v_add_f32_e32 v2, v103, v2
	v_cvt_pk_bf16_f32 v6, v98, v99
	v_cvt_pk_bf16_f32 v7, v100, v101
	s_waitcnt lgkmcnt(13)
	v_mfma_f32_32x32x16_bf16 v[130:145], v[174:177], v[154:157], v[130:145]
	ds_read_b64_tr_b16 v[122:123], v190 offset:38912
	ds_read_b64_tr_b16 v[124:125], v190 offset:39424
	s_waitcnt lgkmcnt(14)
	v_mfma_f32_32x32x16_bf16 v[66:81], v[178:181], v[154:157], v[66:81]
	v_add_f32_e32 v2, v104, v2
	v_add_f32_e32 v2, v105, v2
	v_add_f32_e32 v2, v106, v2
	v_add_f32_e32 v2, v107, v2
	v_cvt_pk_bf16_f32 v8, v102, v103
	v_cvt_pk_bf16_f32 v9, v104, v105
	ds_read_b64_tr_b16 v[102:103], v190 offset:35840
	ds_read_b64_tr_b16 v[104:105], v190 offset:36352
	v_add_f32_e32 v2, v108, v2
	v_add_f32_e32 v2, v109, v2
	v_add_f32_e32 v2, v110, v2
	v_add_f32_e32 v98, v111, v2
	v_cvt_pk_bf16_f32 v2, v106, v107
	v_cvt_pk_bf16_f32 v3, v108, v109
	s_waitcnt lgkmcnt(14)
	v_mfma_f32_32x32x16_bf16 v[130:145], v[90:93], v[150:153], v[130:145]
	ds_read_b64_tr_b16 v[90:91], v190 offset:39936
	ds_read_b64_tr_b16 v[92:93], v190 offset:40448
	v_mfma_f32_32x32x16_bf16 v[66:81], v[82:85], v[150:153], v[66:81]
	v_add_f32_e32 v4, v112, v98
	v_add_f32_e32 v4, v113, v4
	v_add_f32_e32 v82, 0, v4
	v_cvt_pk_bf16_f32 v4, v110, v111
	v_cvt_pk_bf16_f32 v5, v112, v113
	s_add_u32 s14, s14, 0x24d8000
	s_addc_u32 s15, s15, 0
	s_add_i32 s21, s22, 0x4000
	s_mov_b32 s23, m0
	s_mov_b32 m0, s21
	s_nop 0
	global_load_lds_dwordx4 v193, s[14:15]
	s_mov_b32 m0, s23
	s_add_u32 s14, s12, 0x2448000
	s_addc_u32 s15, s13, 0
	s_mov_b32 s21, m0
	s_mov_b32 m0, s20
	s_nop 0
	global_load_lds_dwordx4 v192, s[14:15]
	s_mov_b32 m0, s21
	v_add_f32_e32 v194, v194, v82
	s_waitcnt lgkmcnt(14)
	v_mfma_f32_32x32x16_bf16 v[18:33], v[146:149], v[182:185], v[18:33]
	v_exp_f32_e32 v130, v130
	v_exp_f32_e32 v131, v131
	v_exp_f32_e32 v132, v132
	v_exp_f32_e32 v133, v133
	s_waitcnt lgkmcnt(12)
	v_mfma_f32_32x32x16_bf16 v[34:49], v[146:149], v[114:117], v[34:49]
	v_exp_f32_e32 v134, v134
	v_exp_f32_e32 v135, v135
	v_exp_f32_e32 v136, v136
	v_exp_f32_e32 v137, v137
	ds_read_b128 v[82:85], v191
	ds_read_b128 v[106:109], v191 offset:512
	s_waitcnt lgkmcnt(12)
	v_mfma_f32_32x32x16_bf16 v[18:33], v[10:13], v[86:89], v[18:33]
	v_exp_f32_e32 v138, v138
	v_exp_f32_e32 v139, v139
	v_exp_f32_e32 v140, v140
	v_exp_f32_e32 v141, v141
	ds_read_b128 v[110:113], v191 offset:2048
	ds_read_b128 v[166:169], v191 offset:2560
	s_waitcnt lgkmcnt(12)
	v_mfma_f32_32x32x16_bf16 v[34:49], v[10:13], v[94:97], v[34:49]
	v_exp_f32_e32 v142, v142
	v_exp_f32_e32 v143, v143
	v_exp_f32_e32 v144, v144
	v_exp_f32_e32 v145, v145
	ds_read_b128 v[170:173], v191 offset:4096
	ds_read_b128 v[174:177], v191 offset:4608
	s_waitcnt lgkmcnt(12)
	v_mfma_f32_32x32x16_bf16 v[18:33], v[6:9], v[118:121], v[18:33]
	v_exp_f32_e32 v66, v66
	v_exp_f32_e32 v67, v67
	v_exp_f32_e32 v68, v68
	v_exp_f32_e32 v69, v69
	ds_read_b128 v[178:181], v191 offset:6144
	ds_read_b128 v[98:101], v191 offset:6656
	s_waitcnt lgkmcnt(12)
	v_mfma_f32_32x32x16_bf16 v[34:49], v[6:9], v[122:125], v[34:49]
	v_exp_f32_e32 v70, v70
	v_exp_f32_e32 v71, v71
	v_exp_f32_e32 v72, v72
	v_exp_f32_e32 v73, v73
	s_waitcnt lgkmcnt(10)
	v_mfma_f32_32x32x16_bf16 v[18:33], v[2:5], v[102:105], v[18:33]
	v_exp_f32_e32 v74, v74
	v_exp_f32_e32 v75, v75
	v_exp_f32_e32 v76, v76
	v_exp_f32_e32 v77, v77
	s_waitcnt lgkmcnt(8)
	v_mfma_f32_32x32x16_bf16 v[34:49], v[2:5], v[90:93], v[34:49]
	v_exp_f32_e32 v78, v78
	v_exp_f32_e32 v79, v79
	v_exp_f32_e32 v80, v80
	v_exp_f32_e32 v81, v81
	s_waitcnt vmcnt(2) lgkmcnt(0)
	s_barrier
	ds_read_b64_tr_b16 v[102:103], v190 offset:40960
	ds_read_b64_tr_b16 v[104:105], v190 offset:41472
	v_add_f32_e32 v2, v130, v131
	v_add_f32_e32 v2, v132, v2
	v_add_f32_e32 v2, v133, v2
	v_add_f32_e32 v2, v134, v2
	v_add_f32_e32 v2, v135, v2
	v_cvt_pk_bf16_f32 v146, v130, v131
	v_cvt_pk_bf16_f32 v147, v132, v133
	s_waitcnt lgkmcnt(9)
	v_mfma_f32_32x32x16_bf16 v[114:129], v[82:85], v[162:165], v[50:65]
	ds_read_b64_tr_b16 v[130:131], v190 offset:45056
	ds_read_b64_tr_b16 v[132:133], v190 offset:45568
	v_add_f32_e32 v2, v136, v2
	v_add_f32_e32 v2, v137, v2
	v_add_f32_e32 v2, v138, v2
	v_add_f32_e32 v2, v139, v2
	v_cvt_pk_bf16_f32 v148, v134, v135
	v_cvt_pk_bf16_f32 v149, v136, v137
	s_waitcnt lgkmcnt(10)
	v_mfma_f32_32x32x16_bf16 v[82:97], v[106:109], v[162:165], v[50:65]
	ds_read_b64_tr_b16 v[106:107], v190 offset:41984
	ds_read_b64_tr_b16 v[108:109], v190 offset:42496
	v_add_f32_e32 v2, v140, v2
	v_add_f32_e32 v2, v141, v2
	v_add_f32_e32 v2, v142, v2
	v_add_f32_e32 v2, v143, v2
	v_cvt_pk_bf16_f32 v10, v138, v139
	v_cvt_pk_bf16_f32 v11, v140, v141
	s_waitcnt lgkmcnt(11)
	v_mfma_f32_32x32x16_bf16 v[114:129], v[110:113], v[158:161], v[114:129]
	ds_read_b64_tr_b16 v[110:111], v190 offset:46080
	ds_read_b64_tr_b16 v[112:113], v190 offset:46592
	v_add_f32_e32 v2, v144, v2
	v_add_f32_e32 v2, v145, v2
	v_add_f32_e32 v2, v66, v2
	v_add_f32_e32 v2, v67, v2
	v_cvt_pk_bf16_f32 v12, v142, v143
	v_cvt_pk_bf16_f32 v13, v144, v145
	s_waitcnt lgkmcnt(12)
	v_mfma_f32_32x32x16_bf16 v[82:97], v[166:169], v[158:161], v[82:97]
	ds_read_b64_tr_b16 v[134:135], v190 offset:43008
	ds_read_b64_tr_b16 v[136:137], v190 offset:43520
	v_add_f32_e32 v2, v68, v2
	v_add_f32_e32 v2, v69, v2
	v_add_f32_e32 v2, v70, v2
	v_add_f32_e32 v2, v71, v2
	v_cvt_pk_bf16_f32 v6, v66, v67
	v_cvt_pk_bf16_f32 v7, v68, v69
	s_waitcnt lgkmcnt(13)
	v_mfma_f32_32x32x16_bf16 v[114:129], v[170:173], v[154:157], v[114:129]
	ds_read_b64_tr_b16 v[66:67], v190 offset:47104
	ds_read_b64_tr_b16 v[68:69], v190 offset:47616
	v_add_f32_e32 v2, v72, v2
	v_add_f32_e32 v2, v73, v2
	v_add_f32_e32 v2, v74, v2
	v_add_f32_e32 v2, v75, v2
	v_cvt_pk_bf16_f32 v8, v70, v71
	v_cvt_pk_bf16_f32 v9, v72, v73
	s_waitcnt lgkmcnt(14)
	v_mfma_f32_32x32x16_bf16 v[82:97], v[174:177], v[154:157], v[82:97]
	ds_read_b64_tr_b16 v[70:71], v190 offset:44032
	ds_read_b64_tr_b16 v[72:73], v190 offset:44544
	v_add_f32_e32 v2, v76, v2
	v_add_f32_e32 v2, v77, v2
	v_add_f32_e32 v2, v78, v2
	v_add_f32_e32 v138, v79, v2
	v_cvt_pk_bf16_f32 v2, v74, v75
	v_cvt_pk_bf16_f32 v3, v76, v77
	s_waitcnt lgkmcnt(14)
	v_mfma_f32_32x32x16_bf16 v[114:129], v[178:181], v[150:153], v[114:129]
	ds_read_b64_tr_b16 v[74:75], v190 offset:48128
	ds_read_b64_tr_b16 v[76:77], v190 offset:48640
	v_add_f32_e32 v4, v80, v138
	v_add_f32_e32 v4, v81, v4
	v_mfma_f32_32x32x16_bf16 v[82:97], v[98:101], v[150:153], v[82:97]
	v_add_f32_e32 v98, 0, v4
	v_cvt_pk_bf16_f32 v4, v78, v79
	v_cvt_pk_bf16_f32 v5, v80, v81
	s_add_u32 s14, s12, 0x2490000
	s_addc_u32 s15, s13, 0
	s_add_i32 s22, s22, 0x8000
	s_mov_b32 s20, m0
	s_mov_b32 m0, s22
	s_nop 0
	global_load_lds_dwordx4 v192, s[14:15]
	s_mov_b32 m0, s20
	v_add_f32_e32 v182, v194, v98
	s_waitcnt lgkmcnt(14)
	v_mfma_f32_32x32x16_bf16 v[18:33], v[146:149], v[102:105], v[18:33]
	v_exp_f32_e32 v114, v114
	v_exp_f32_e32 v115, v115
	v_exp_f32_e32 v116, v116
	v_exp_f32_e32 v117, v117
	s_waitcnt lgkmcnt(12)
	v_mfma_f32_32x32x16_bf16 v[34:49], v[146:149], v[130:133], v[34:49]
	v_exp_f32_e32 v118, v118
	v_exp_f32_e32 v119, v119
	v_exp_f32_e32 v120, v120
	v_exp_f32_e32 v121, v121
	ds_read_b128 v[78:81], v191 offset:8192
	ds_read_b128 v[138:141], v191 offset:8704
	s_waitcnt lgkmcnt(12)
	v_mfma_f32_32x32x16_bf16 v[18:33], v[10:13], v[106:109], v[18:33]
	v_exp_f32_e32 v122, v122
	v_exp_f32_e32 v123, v123
	v_exp_f32_e32 v124, v124
	v_exp_f32_e32 v125, v125
	ds_read_b128 v[142:145], v191 offset:10240
	ds_read_b128 v[166:169], v191 offset:10752
	s_waitcnt lgkmcnt(12)
	v_mfma_f32_32x32x16_bf16 v[34:49], v[10:13], v[110:113], v[34:49]
	v_exp_f32_e32 v126, v126
	v_exp_f32_e32 v127, v127
	v_exp_f32_e32 v128, v128
	v_exp_f32_e32 v129, v129
	ds_read_b128 v[170:173], v191 offset:12288
	ds_read_b128 v[174:177], v191 offset:12800
	s_waitcnt lgkmcnt(12)
	v_mfma_f32_32x32x16_bf16 v[18:33], v[6:9], v[134:137], v[18:33]
	v_exp_f32_e32 v82, v82
	v_exp_f32_e32 v83, v83
	v_exp_f32_e32 v84, v84
	v_exp_f32_e32 v85, v85
	ds_read_b128 v[134:137], v191 offset:14336
	ds_read_b128 v[130:133], v191 offset:14848
	s_waitcnt lgkmcnt(12)
	v_mfma_f32_32x32x16_bf16 v[34:49], v[6:9], v[66:69], v[34:49]
	v_exp_f32_e32 v86, v86
	v_exp_f32_e32 v87, v87
	v_exp_f32_e32 v88, v88
	v_exp_f32_e32 v89, v89
	s_waitcnt lgkmcnt(10)
	v_mfma_f32_32x32x16_bf16 v[18:33], v[2:5], v[70:73], v[18:33]
	v_exp_f32_e32 v90, v90
	v_exp_f32_e32 v91, v91
	v_exp_f32_e32 v92, v92
	v_exp_f32_e32 v93, v93
	s_waitcnt lgkmcnt(8)
	v_mfma_f32_32x32x16_bf16 v[34:49], v[2:5], v[74:77], v[34:49]
	v_exp_f32_e32 v94, v94
	v_exp_f32_e32 v95, v95
	v_exp_f32_e32 v96, v96
	v_exp_f32_e32 v97, v97
	s_waitcnt vmcnt(1) lgkmcnt(0)
	s_barrier
	ds_read_b64_tr_b16 v[178:179], v190 offset:24576
	ds_read_b64_tr_b16 v[180:181], v190 offset:25088
	v_add_f32_e32 v2, v114, v115
	v_add_f32_e32 v2, v116, v2
	v_add_f32_e32 v2, v117, v2
	v_add_f32_e32 v2, v118, v2
	v_add_f32_e32 v2, v119, v2
	v_cvt_pk_bf16_f32 v146, v114, v115
	v_cvt_pk_bf16_f32 v147, v116, v117
	s_waitcnt lgkmcnt(9)
	v_mfma_f32_32x32x16_bf16 v[98:113], v[78:81], v[162:165], v[50:65]
	ds_read_b64_tr_b16 v[114:115], v190 offset:28672
	ds_read_b64_tr_b16 v[116:117], v190 offset:29184
	s_waitcnt lgkmcnt(10)
	v_mfma_f32_32x32x16_bf16 v[66:81], v[138:141], v[162:165], v[50:65]
	v_add_f32_e32 v2, v120, v2
	v_add_f32_e32 v2, v121, v2
	v_add_f32_e32 v2, v122, v2
	v_add_f32_e32 v2, v123, v2
	v_cvt_pk_bf16_f32 v148, v118, v119
	v_cvt_pk_bf16_f32 v149, v120, v121
	ds_read_b64_tr_b16 v[118:119], v190 offset:25600
	ds_read_b64_tr_b16 v[120:121], v190 offset:26112
	v_add_f32_e32 v2, v124, v2
	v_add_f32_e32 v2, v125, v2
	v_add_f32_e32 v2, v126, v2
	v_add_f32_e32 v2, v127, v2
	v_cvt_pk_bf16_f32 v10, v122, v123
	v_cvt_pk_bf16_f32 v11, v124, v125
	s_waitcnt lgkmcnt(11)
	v_mfma_f32_32x32x16_bf16 v[98:113], v[142:145], v[158:161], v[98:113]
	ds_read_b64_tr_b16 v[122:123], v190 offset:29696
	ds_read_b64_tr_b16 v[124:125], v190 offset:30208
	s_waitcnt lgkmcnt(12)
	v_mfma_f32_32x32x16_bf16 v[66:81], v[166:169], v[158:161], v[66:81]
	v_add_f32_e32 v2, v128, v2
	v_add_f32_e32 v2, v129, v2
	v_add_f32_e32 v2, v82, v2
	v_add_f32_e32 v2, v83, v2
	v_cvt_pk_bf16_f32 v12, v126, v127
	v_cvt_pk_bf16_f32 v13, v128, v129
	ds_read_b64_tr_b16 v[138:139], v190 offset:26624
	ds_read_b64_tr_b16 v[140:141], v190 offset:27136
	v_add_f32_e32 v2, v84, v2
	v_add_f32_e32 v2, v85, v2
	v_add_f32_e32 v2, v86, v2
	v_add_f32_e32 v2, v87, v2
	v_cvt_pk_bf16_f32 v6, v82, v83
	v_cvt_pk_bf16_f32 v7, v84, v85
	s_waitcnt lgkmcnt(13)
	v_mfma_f32_32x32x16_bf16 v[98:113], v[170:173], v[154:157], v[98:113]
	ds_read_b64_tr_b16 v[82:83], v190 offset:30720
	ds_read_b64_tr_b16 v[84:85], v190 offset:31232
	s_waitcnt lgkmcnt(14)
	v_mfma_f32_32x32x16_bf16 v[66:81], v[174:177], v[154:157], v[66:81]
	v_add_f32_e32 v2, v88, v2
	v_add_f32_e32 v2, v89, v2
	v_add_f32_e32 v2, v90, v2
	v_add_f32_e32 v2, v91, v2
	v_cvt_pk_bf16_f32 v8, v86, v87
	v_cvt_pk_bf16_f32 v9, v88, v89
	ds_read_b64_tr_b16 v[86:87], v190 offset:27648
	ds_read_b64_tr_b16 v[88:89], v190 offset:28160
	v_add_f32_e32 v2, v92, v2
	v_add_f32_e32 v2, v93, v2
	v_add_f32_e32 v2, v94, v2
	v_add_f32_e32 v126, v95, v2
	v_cvt_pk_bf16_f32 v2, v90, v91
	v_cvt_pk_bf16_f32 v3, v92, v93
	s_waitcnt lgkmcnt(14)
	v_mfma_f32_32x32x16_bf16 v[98:113], v[134:137], v[150:153], v[98:113]
	ds_read_b64_tr_b16 v[90:91], v190 offset:31744
	ds_read_b64_tr_b16 v[92:93], v190 offset:32256
	v_mfma_f32_32x32x16_bf16 v[66:81], v[130:133], v[150:153], v[66:81]
	v_add_f32_e32 v4, v96, v126
	v_add_f32_e32 v4, v97, v4
	v_add_f32_e32 v126, 0, v4
	v_cvt_pk_bf16_f32 v4, v94, v95
	v_cvt_pk_bf16_f32 v5, v96, v97
	s_add_u32 s12, s12, 0x24d8000
	s_addc_u32 s13, s13, 0
	s_mov_b32 s14, m0
	s_mov_b32 m0, s17
	s_nop 0
	global_load_lds_dwordx4 v192, s[12:13]
	s_mov_b32 m0, s14
	v_add_f32_e32 v126, v182, v126
	s_waitcnt lgkmcnt(14)
	v_mfma_f32_32x32x16_bf16 v[18:33], v[146:149], v[178:181], v[18:33]
	v_exp_f32_e32 v98, v98
	v_exp_f32_e32 v99, v99
	v_exp_f32_e32 v100, v100
	v_exp_f32_e32 v101, v101
	s_waitcnt lgkmcnt(12)
	v_mfma_f32_32x32x16_bf16 v[34:49], v[146:149], v[114:117], v[34:49]
	v_exp_f32_e32 v102, v102
	v_exp_f32_e32 v103, v103
	v_exp_f32_e32 v104, v104
	v_exp_f32_e32 v105, v105
	ds_read_b128 v[128:131], v191 offset:16384
	ds_read_b128 v[132:135], v191 offset:16896
	s_waitcnt lgkmcnt(12)
	v_mfma_f32_32x32x16_bf16 v[18:33], v[10:13], v[118:121], v[18:33]
	v_exp_f32_e32 v106, v106
	v_exp_f32_e32 v107, v107
	v_exp_f32_e32 v108, v108
	v_exp_f32_e32 v109, v109
	ds_read_b128 v[142:145], v191 offset:18432
	ds_read_b128 v[166:169], v191 offset:18944
	s_waitcnt lgkmcnt(12)
	v_mfma_f32_32x32x16_bf16 v[34:49], v[10:13], v[122:125], v[34:49]
	v_exp_f32_e32 v110, v110
	v_exp_f32_e32 v111, v111
	v_exp_f32_e32 v112, v112
	v_exp_f32_e32 v113, v113
	ds_read_b128 v[170:173], v191 offset:20480
	ds_read_b128 v[174:177], v191 offset:20992
	s_waitcnt lgkmcnt(12)
	v_mfma_f32_32x32x16_bf16 v[18:33], v[6:9], v[138:141], v[18:33]
	v_exp_f32_e32 v66, v66
	v_exp_f32_e32 v67, v67
	v_exp_f32_e32 v68, v68
	v_exp_f32_e32 v69, v69
	ds_read_b128 v[136:139], v191 offset:22528
	ds_read_b128 v[122:125], v191 offset:23040
	s_waitcnt lgkmcnt(12)
	v_mfma_f32_32x32x16_bf16 v[34:49], v[6:9], v[82:85], v[34:49]
	v_exp_f32_e32 v70, v70
	v_exp_f32_e32 v71, v71
	v_exp_f32_e32 v72, v72
	v_exp_f32_e32 v73, v73
	s_waitcnt lgkmcnt(10)
	v_mfma_f32_32x32x16_bf16 v[18:33], v[2:5], v[86:89], v[18:33]
	v_exp_f32_e32 v74, v74
	v_exp_f32_e32 v75, v75
	v_exp_f32_e32 v76, v76
	v_exp_f32_e32 v77, v77
	s_waitcnt lgkmcnt(8)
	v_mfma_f32_32x32x16_bf16 v[34:49], v[2:5], v[90:93], v[34:49]
	v_exp_f32_e32 v78, v78
	v_exp_f32_e32 v79, v79
	v_exp_f32_e32 v80, v80
	v_exp_f32_e32 v81, v81
	s_waitcnt vmcnt(0) lgkmcnt(0)
	s_barrier
; #define RESC() do { if (resc) { asm volatile("s_waitcnt lgkmcnt(0)" ::: "memory"); \
;       _Pragma("unroll") for (int d_ = 0; d_ < 2; ++d_) _Pragma("unroll") for (int r = 0; r < 16; ++r) o[d_][r] *= wsf[crow(r, hi)]; } } while (0)
; #define PKW(P, B) cvtpk_s(P[B], P[B + 1])
;     ...
;     STEP(pB0, pB1, pA0, pA1, NT - 1, false, false, false); RESC();
;     { float sacc = pB0[0] + pB0[1]; _Pragma("unroll") for (int r = 2; r < 16; ++r) sacc += pB0[r]; _Pragma("unroll") for (int r = 0; r < 16; ++r) sacc += pB1[r]; l_reg += sacc;
;       pw0 = (u32x4){PKW(pB0, 0), PKW(pB0, 2), PKW(pB0, 4), PKW(pB0, 6)}; pw1 = (u32x4){PKW(pB0, 8), PKW(pB0, 10), PKW(pB0, 12), PKW(pB0, 14)}; pw2 = (u32x4){PKW(pB1, 0), PKW(pB1, 2), PKW(pB1, 4), PKW(pB1, 6)}; pw3 = (u32x4){PKW(pB1, 8), PKW(pB1, 10), PKW(pB1, 12), PKW(pB1, 14)};
	ds_read_b64_tr_b16 v[114:115], v190 offset:32768
	ds_read_b64_tr_b16 v[116:117], v190 offset:33280
	v_add_f32_e32 v2, v98, v99
	v_add_f32_e32 v2, v100, v2
	v_add_f32_e32 v2, v101, v2
	v_add_f32_e32 v2, v102, v2
	v_add_f32_e32 v2, v103, v2
	v_cvt_pk_bf16_f32 v146, v98, v99
	v_cvt_pk_bf16_f32 v147, v100, v101
	s_waitcnt lgkmcnt(9)
	v_mfma_f32_32x32x16_bf16 v[82:97], v[128:131], v[162:165], v[50:65]
	ds_read_b64_tr_b16 v[98:99], v190 offset:36864
	ds_read_b64_tr_b16 v[100:101], v190 offset:37376
	v_add_f32_e32 v2, v104, v2
	v_add_f32_e32 v2, v105, v2
	v_add_f32_e32 v2, v106, v2
	v_add_f32_e32 v2, v107, v2
	v_cvt_pk_bf16_f32 v148, v102, v103
	v_cvt_pk_bf16_f32 v149, v104, v105
	s_waitcnt lgkmcnt(10)
	v_mfma_f32_32x32x16_bf16 v[50:65], v[132:135], v[162:165], v[50:65]
	ds_read_b64_tr_b16 v[118:119], v190 offset:33792
	ds_read_b64_tr_b16 v[120:121], v190 offset:34304
	v_add_f32_e32 v2, v108, v2
	v_add_f32_e32 v2, v109, v2
	v_add_f32_e32 v2, v110, v2
	v_add_f32_e32 v2, v111, v2
	v_cvt_pk_bf16_f32 v10, v106, v107
	v_cvt_pk_bf16_f32 v11, v108, v109
	s_waitcnt lgkmcnt(11)
	v_mfma_f32_32x32x16_bf16 v[82:97], v[142:145], v[158:161], v[82:97]
	ds_read_b64_tr_b16 v[102:103], v190 offset:37888
	ds_read_b64_tr_b16 v[104:105], v190 offset:38400
	v_add_f32_e32 v2, v112, v2
	v_add_f32_e32 v2, v113, v2
	v_add_f32_e32 v2, v66, v2
	v_add_f32_e32 v2, v67, v2
	v_cvt_pk_bf16_f32 v12, v110, v111
	v_cvt_pk_bf16_f32 v13, v112, v113
	s_waitcnt lgkmcnt(12)
	v_mfma_f32_32x32x16_bf16 v[50:65], v[166:169], v[158:161], v[50:65]
	ds_read_b64_tr_b16 v[106:107], v190 offset:34816
	ds_read_b64_tr_b16 v[108:109], v190 offset:35328
	v_add_f32_e32 v2, v68, v2
	v_add_f32_e32 v2, v69, v2
	v_add_f32_e32 v2, v70, v2
	v_add_f32_e32 v2, v71, v2
	v_cvt_pk_bf16_f32 v6, v66, v67
	v_cvt_pk_bf16_f32 v7, v68, v69
	s_waitcnt lgkmcnt(13)
	v_mfma_f32_32x32x16_bf16 v[82:97], v[170:173], v[154:157], v[82:97]
	ds_read_b64_tr_b16 v[66:67], v190 offset:38912
	ds_read_b64_tr_b16 v[68:69], v190 offset:39424
	v_add_f32_e32 v2, v72, v2
	v_add_f32_e32 v2, v73, v2
	v_add_f32_e32 v2, v74, v2
	v_add_f32_e32 v2, v75, v2
	v_cvt_pk_bf16_f32 v8, v70, v71
	v_cvt_pk_bf16_f32 v9, v72, v73
	s_waitcnt lgkmcnt(14)
	v_mfma_f32_32x32x16_bf16 v[50:65], v[174:177], v[154:157], v[50:65]
	ds_read_b64_tr_b16 v[110:111], v190 offset:35840
	ds_read_b64_tr_b16 v[112:113], v190 offset:36352
	v_add_f32_e32 v2, v76, v2
	v_add_f32_e32 v2, v77, v2
	v_add_f32_e32 v2, v78, v2
	v_add_f32_e32 v127, v79, v2
	v_cvt_pk_bf16_f32 v2, v74, v75
	v_cvt_pk_bf16_f32 v3, v76, v77
	s_waitcnt lgkmcnt(14)
	v_mfma_f32_32x32x16_bf16 v[82:97], v[136:139], v[150:153], v[82:97]
	ds_read_b64_tr_b16 v[70:71], v190 offset:39936
	ds_read_b64_tr_b16 v[72:73], v190 offset:40448
	v_add_f32_e32 v4, v80, v127
	v_add_f32_e32 v4, v81, v4
	v_add_f32_e32 v74, 0, v4
	v_cvt_pk_bf16_f32 v4, v78, v79
	v_cvt_pk_bf16_f32 v5, v80, v81
	v_mfma_f32_32x32x16_bf16 v[50:65], v[122:125], v[150:153], v[50:65]
	s_nop 3
	v_exp_f32_e32 v82, v82
	v_exp_f32_e32 v83, v83
	v_exp_f32_e32 v84, v84
	v_exp_f32_e32 v85, v85
	s_nop 0
	v_exp_f32_e32 v86, v86
	v_exp_f32_e32 v87, v87
	v_exp_f32_e32 v88, v88
	v_exp_f32_e32 v89, v89
	s_nop 0
	v_exp_f32_e32 v90, v90
	v_exp_f32_e32 v91, v91
	v_exp_f32_e32 v92, v92
	v_exp_f32_e32 v93, v93
	s_nop 0
	v_exp_f32_e32 v94, v94
	v_exp_f32_e32 v95, v95
	v_exp_f32_e32 v96, v96
	v_exp_f32_e32 v97, v97
	v_exp_f32_e32 v50, v50
	v_exp_f32_e32 v51, v51
	v_exp_f32_e32 v52, v52
	v_exp_f32_e32 v53, v53
	s_nop 0
	v_exp_f32_e32 v54, v54
	v_exp_f32_e32 v55, v55
	v_exp_f32_e32 v56, v56
	v_exp_f32_e32 v57, v57
	s_nop 0
	v_exp_f32_e32 v58, v58
	v_exp_f32_e32 v59, v59
	v_exp_f32_e32 v60, v60
	v_exp_f32_e32 v61, v61
	s_nop 0
	v_exp_f32_e32 v62, v62
	v_exp_f32_e32 v63, v63
	v_exp_f32_e32 v64, v64
	v_exp_f32_e32 v65, v65
	s_waitcnt lgkmcnt(14)
	v_mfma_f32_32x32x16_bf16 v[18:33], v[146:149], v[114:117], v[18:33]
	v_add_f32_e32 v75, v82, v83
	v_add_f32_e32 v75, v84, v75
	v_add_f32_e32 v75, v85, v75
	v_add_f32_e32 v75, v86, v75
	v_add_f32_e32 v75, v87, v75
	v_add_f32_e32 v75, v88, v75
	v_add_f32_e32 v75, v89, v75
	s_waitcnt lgkmcnt(12)
	v_mfma_f32_32x32x16_bf16 v[34:49], v[146:149], v[98:101], v[34:49]
	v_add_f32_e32 v75, v90, v75
	v_add_f32_e32 v75, v91, v75
	v_add_f32_e32 v75, v92, v75
	v_add_f32_e32 v75, v93, v75
	v_add_f32_e32 v75, v94, v75
	v_add_f32_e32 v75, v95, v75
	v_add_f32_e32 v75, v96, v75
	s_waitcnt lgkmcnt(10)
; #define AT_SBAR() __builtin_amdgcn_sched_barrier(0)
; #define SBAR() __builtin_amdgcn_sched_barrier(0)
; #define RESC() do { if (resc) { asm volatile("s_waitcnt lgkmcnt(0)" ::: "memory"); \
;       _Pragma("unroll") for (int d_ = 0; d_ < 2; ++d_) _Pragma("unroll") for (int r = 0; r < 16; ++r) o[d_][r] *= wsf[crow(r, hi)]; } } while (0)
; #define PKW(P, B) cvtpk_s(P[B], P[B + 1])
; __device__ __forceinline__ void pv(f32x16* o, int vb, bf16x8 pa0, bf16x8 pa1, bf16x8 pa2, bf16x8 pa3) {
; #pragma unroll
;     for (int d0 = 0; d0 < 2; ++d0) { s16x4 lo[4], hi[4];
; #pragma unroll
;         for (int ks = 0; ks < 4; ++ks) {
;             asm volatile("ds_read_b64_tr_b16 %0,%1 offset:%c2" : "=&v"(lo[ks]) : "v"(vb), "i"(d0 * 4096 + ks * 1024) : "memory");
;             asm volatile("ds_read_b64_tr_b16 %0,%1 offset:%c2" : "=&v"(hi[ks]) : "v"(vb), "i"(d0 * 4096 + ks * 1024 + 512) : "memory"); }
;         asm volatile("s_waitcnt lgkmcnt(0)" ::: "memory"); AT_SBAR();
;     ...
;         o[d0] = __builtin_amdgcn_mfma_f32_32x32x16_bf16(pa0, AT_PK(0), o[d0], 0, 0, 0);
;         o[d0] = __builtin_amdgcn_mfma_f32_32x32x16_bf16(pa1, AT_PK(1), o[d0], 0, 0, 0);
;         o[d0] = __builtin_amdgcn_mfma_f32_32x32x16_bf16(pa2, AT_PK(2), o[d0], 0, 0, 0);
;         o[d0] = __builtin_amdgcn_mfma_f32_32x32x16_bf16(pa3, AT_PK(3), o[d0], 0, 0, 0);
;     ...
;     STEP(pB0, pB1, pA0, pA1, NT - 1, false, false, false); RESC();
;     { float sacc = pB0[0] + pB0[1]; _Pragma("unroll") for (int r = 2; r < 16; ++r) sacc += pB0[r]; _Pragma("unroll") for (int r = 0; r < 16; ++r) sacc += pB1[r]; l_reg += sacc;
;       pw0 = (u32x4){PKW(pB0, 0), PKW(pB0, 2), PKW(pB0, 4), PKW(pB0, 6)}; pw1 = (u32x4){PKW(pB0, 8), PKW(pB0, 10), PKW(pB0, 12), PKW(pB0, 14)}; pw2 = (u32x4){PKW(pB1, 0), PKW(pB1, 2), PKW(pB1, 4), PKW(pB1, 6)}; pw3 = (u32x4){PKW(pB1, 8), PKW(pB1, 10), PKW(pB1, 12), PKW(pB1, 14)};
;       SBAR(); const int vb0 = (int)(lds0 + LDS_V) + ((lane >> 4) & 1) * 32 + (lane & 3) * 8 + (4 * hi + ((lane & 15) >> 2)) * 64;
;       at::pv(o, vb0 + sl_cur, PAF(0), PAF(1), PAF(2), PAF(3)); }
	v_mfma_f32_32x32x16_bf16 v[18:33], v[10:13], v[118:121], v[18:33]
	v_add_f32_e32 v75, v97, v75
	v_add_f32_e32 v75, v50, v75
	v_add_f32_e32 v75, v51, v75
	v_add_f32_e32 v75, v52, v75
	v_add_f32_e32 v75, v53, v75
	v_add_f32_e32 v75, v54, v75
	v_add_f32_e32 v75, v55, v75
	s_waitcnt lgkmcnt(8)
	v_mfma_f32_32x32x16_bf16 v[34:49], v[10:13], v[102:105], v[34:49]
	v_add_f32_e32 v75, v56, v75
	v_add_f32_e32 v75, v57, v75
	v_add_f32_e32 v75, v58, v75
	v_add_f32_e32 v75, v59, v75
	v_add_f32_e32 v75, v60, v75
	v_add_f32_e32 v75, v61, v75
	v_add_f32_e32 v75, v62, v75
	s_waitcnt lgkmcnt(6)
	v_mfma_f32_32x32x16_bf16 v[18:33], v[6:9], v[106:109], v[18:33]
	v_add_f32_e32 v75, v63, v75
	v_add_f32_e32 v75, v64, v75
	v_add_f32_e32 v75, v65, v75
	v_add_f32_e32 v74, v126, v74
	v_add_f32_e32 v74, v74, v75
	v_cvt_pk_bf16_f32 v76, v82, v83
	v_cvt_pk_bf16_f32 v77, v84, v85
	s_waitcnt lgkmcnt(4)
	v_mfma_f32_32x32x16_bf16 v[34:49], v[6:9], v[66:69], v[34:49]
	v_cvt_pk_bf16_f32 v78, v86, v87
	v_cvt_pk_bf16_f32 v79, v88, v89
	v_cvt_pk_bf16_f32 v10, v90, v91
	v_cvt_pk_bf16_f32 v11, v92, v93
	v_cvt_pk_bf16_f32 v12, v94, v95
	v_cvt_pk_bf16_f32 v13, v96, v97
	v_cvt_pk_bf16_f32 v6, v50, v51
	s_waitcnt lgkmcnt(2)
	v_mfma_f32_32x32x16_bf16 v[18:33], v[2:5], v[110:113], v[18:33]
	v_cvt_pk_bf16_f32 v7, v52, v53
	v_cvt_pk_bf16_f32 v8, v54, v55
	v_cvt_pk_bf16_f32 v9, v56, v57
	v_cvt_pk_bf16_f32 v50, v58, v59
	v_cvt_pk_bf16_f32 v51, v60, v61
	v_cvt_pk_bf16_f32 v52, v62, v63
	v_cvt_pk_bf16_f32 v53, v64, v65
	s_waitcnt lgkmcnt(0)
	v_mfma_f32_32x32x16_bf16 v[34:49], v[2:5], v[70:73], v[34:49]
	v_add_u32_e32 v2, s16, v188
	v_add3_u32 v66, v2, v187, v189
	ds_read_b64_tr_b16 v[2:3],v66 offset:0
	ds_read_b64_tr_b16 v[4:5],v66 offset:512
	ds_read_b64_tr_b16 v[54:55],v66 offset:1024
	ds_read_b64_tr_b16 v[56:57],v66 offset:1536
	ds_read_b64_tr_b16 v[58:59],v66 offset:2048
	ds_read_b64_tr_b16 v[60:61],v66 offset:2560
	ds_read_b64_tr_b16 v[62:63],v66 offset:3072
	ds_read_b64_tr_b16 v[64:65],v66 offset:3584
	s_waitcnt lgkmcnt(0)
	s_nop 0
	v_mfma_f32_32x32x16_bf16 v[18:33], v[76:79], v[2:5], v[18:33]
	ds_read_b64_tr_b16 v[2:3],v66 offset:4096
	ds_read_b64_tr_b16 v[4:5],v66 offset:4608
	v_mfma_f32_32x32x16_bf16 v[18:33], v[10:13], v[54:57], v[18:33]
	ds_read_b64_tr_b16 v[54:55],v66 offset:5120
	ds_read_b64_tr_b16 v[56:57],v66 offset:5632
	v_mfma_f32_32x32x16_bf16 v[18:33], v[6:9], v[58:61], v[18:33]
	ds_read_b64_tr_b16 v[58:59],v66 offset:6144
	ds_read_b64_tr_b16 v[60:61],v66 offset:6656
	v_mfma_f32_32x32x16_bf16 v[18:33], v[50:53], v[62:65], v[18:33]
	ds_read_b64_tr_b16 v[62:63],v66 offset:7168
	ds_read_b64_tr_b16 v[64:65],v66 offset:7680
	s_waitcnt lgkmcnt(0)
	v_mfma_f32_32x32x16_bf16 v[34:49], v[76:79], v[2:5], v[34:49]
	v_mfma_f32_32x32x16_bf16 v[34:49], v[10:13], v[54:57], v[34:49]
	v_mfma_f32_32x32x16_bf16 v[34:49], v[6:9], v[58:61], v[34:49]
	v_mfma_f32_32x32x16_bf16 v[34:49], v[50:53], v[62:65], v[34:49]
	s_cmp_eq_u32 s101, 2
	s_cbranch_scc1 .Lgc_full
	s_nop 15
	s_sub_i32 s38, s48, 0x100
	s_lshl_b32 s40, s38, 6
	s_add_u32 s42, s76, 0x10000
	s_addc_u32 s43, s77, 0
	s_add_u32 s42, s42, s40
	s_addc_u32 s43, s43, 0
	s_mul_i32 s40, s38, 0x11000
	s_mul_i32 s39, s19, 0x2200
	s_add_u32 s40, s40, s39
	s_add_u32 s36, s76, 0xa200000
	s_addc_u32 s37, s77, 0
	s_add_u32 s36, s36, s40
	s_addc_u32 s37, s37, 0
	s_add_u32 s44, s36, 0x1000
	s_addc_u32 s45, s37, 0
	v_lshlrev_b32_e32 v116, 4, v15
	v_lshlrev_b32_e32 v115, 2, v15
	v_add_u32_e32 v115, 0x1000, v115
	v_mov_b32_e32 v120, 1
	s_cmp_eq_u32 s101, 1
	s_cbranch_scc1 .Lgc_second
	global_store_dwordx4 v116, v[18:21], s[36:37] sc0 sc1
	global_store_dwordx4 v116, v[22:25], s[36:37] offset:1024 sc0 sc1
	global_store_dwordx4 v116, v[26:29], s[36:37] offset:2048 sc0 sc1
	global_store_dwordx4 v116, v[30:33], s[36:37] offset:3072 sc0 sc1
	global_store_dwordx4 v116, v[34:37], s[44:45] sc0 sc1
	global_store_dwordx4 v116, v[38:41], s[44:45] offset:1024 sc0 sc1
	global_store_dwordx4 v116, v[42:45], s[44:45] offset:2048 sc0 sc1
	global_store_dwordx4 v116, v[46:49], s[44:45] offset:3072 sc0 sc1
	global_store_dword v115, v74, s[44:45] sc0 sc1
	s_waitcnt vmcnt(0)
	s_barrier
	s_and_saveexec_b64 s[44:45], s[62:63]
	s_cbranch_execz .Lgc_f1
	v_mov_b32_e32 v118, s42
	v_mov_b32_e32 v119, s43
	flat_atomic_add v[118:119], v120

; __device__ __forceinline__ unsigned xb_ld(unsigned* p)              { return __hip_atomic_load(p, __ATOMIC_RELAXED, __HIP_MEMORY_SCOPE_AGENT); }
; __device__ __forceinline__ void wait_cnt(unsigned* c, unsigned target) {
;     if (threadIdx.x == 0) {
;         unsigned sp = 0u; while (xb_ld(c) < target) { __builtin_amdgcn_s_sleep(4); if (++sp > (1u << 24)) break; }
;         __builtin_amdgcn_fence(__ATOMIC_ACQUIRE, "agent"); asm volatile("s_waitcnt vmcnt(0)" ::: "memory");
;     }
;     __syncthreads();
; }
.Lgc_second:
	v_readlane_b32 s41, v252, 9
	s_mov_b64 s[38:39], exec
	s_add_i32 s41, s41, 1
	s_and_b64 exec, exec, s[62:63]
	s_cbranch_execz .Lgc_w_done
	v_mov_b32_e32 v118, s42
	v_mov_b32_e32 v119, s43
	s_mov_b32 s40, 0x4000
.Lgc_spin:
	flat_load_dword v117, v[118:119] sc1
	s_waitcnt vmcnt(0) lgkmcnt(0)
	v_readfirstlane_b32 s46, v117
	s_nop 3
	s_cmp_ge_u32 s46, s41
	s_cbranch_scc1 .Lgc_spun
	s_sleep 4
	s_sub_u32 s40, s40, 1
	s_cmp_lg_u32 s40, 0
	s_cbranch_scc1 .Lgc_spin

;     ...
;     { auto rr = __builtin_amdgcn_permlane32_swap(__float_as_uint(l_reg), __float_as_uint(l_reg), false, false); l_reg = __uint_as_float(rr[0]) + __uint_as_float(rr[1]); }
;     if (hi == 0) wsf[32 + r32] = l_reg; asm volatile("s_waitcnt lgkmcnt(0)" ::: "memory");
.Lgc_w_done:
	s_mov_b64 exec, s[38:39]
	s_barrier
	global_load_dwordx4 v[82:85], v116, s[36:37]
	global_load_dwordx4 v[86:89], v116, s[36:37] offset:1024
	global_load_dwordx4 v[90:93], v116, s[36:37] offset:2048
	global_load_dwordx4 v[94:97], v116, s[36:37] offset:3072
	global_load_dwordx4 v[98:101], v116, s[44:45]
	global_load_dwordx4 v[102:105], v116, s[44:45] offset:1024
	global_load_dwordx4 v[106:109], v116, s[44:45] offset:2048
	global_load_dwordx4 v[110:113], v116, s[44:45] offset:3072
	global_load_dword v114, v115, s[44:45]
	s_waitcnt vmcnt(0)
	v_pk_add_f32 v[18:19], v[18:19], v[82:83]
	v_pk_add_f32 v[20:21], v[20:21], v[84:85]
	v_pk_add_f32 v[22:23], v[22:23], v[86:87]
	v_pk_add_f32 v[24:25], v[24:25], v[88:89]
	v_pk_add_f32 v[26:27], v[26:27], v[90:91]
	v_pk_add_f32 v[28:29], v[28:29], v[92:93]
	v_pk_add_f32 v[30:31], v[30:31], v[94:95]
	v_pk_add_f32 v[32:33], v[32:33], v[96:97]
	v_pk_add_f32 v[34:35], v[34:35], v[98:99]
	v_pk_add_f32 v[36:37], v[36:37], v[100:101]
	v_pk_add_f32 v[38:39], v[38:39], v[102:103]
	v_pk_add_f32 v[40:41], v[40:41], v[104:105]
	v_pk_add_f32 v[42:43], v[42:43], v[106:107]
	v_pk_add_f32 v[44:45], v[44:45], v[108:109]
	v_pk_add_f32 v[46:47], v[46:47], v[110:111]
	v_pk_add_f32 v[48:49], v[48:49], v[112:113]
	v_add_f32_e32 v74, v74, v114
; __device__ __forceinline__ int crow(int r, int hi) { return (r & 3) + 8 * (r >> 2) + 4 * hi; }
; __device__ __forceinline__ unsigned cvtpk_s(float lo, float hi) { typedef __bf16 bf16x2_t __attribute__((ext_vector_type(2))); f32x2 v = {lo, hi}; bf16x2_t b = __builtin_convertvector(v, bf16x2_t); return __builtin_bit_cast(unsigned, b); }
; __device__ __forceinline__ void store_tile(const f32x16* o, const float* rli, bf16_t* stg, bf16_t* Ow, int pitch, float* ss, int lane, int r32, int hi) {
; #pragma unroll
;     for (int r = 0; r < 16; ++r) { const int orow = crow(r, hi);
; #pragma unroll
;         for (int d0 = 0; d0 < 2; ++d0) stg[orow * 64 + d0 * 32 + r32] = (bf16_t)(cvtpk_s(o[d0][r] * rli[r], 0.f) & 0xffffu); }
;     asm volatile("s_waitcnt lgkmcnt(0)" ::: "memory");
; #pragma unroll
;     for (int i = 0; i < 4; ++i) { const int row = i * 8 + (lane >> 3), ch = lane & 7; const u32x4 v = *(const u32x4*)(stg + row * 64 + ch * 8);
;         { const bf16_t* gp_ = Ow + (long)row * pitch + ch * 8; asm volatile("global_store_dwordx4 %0, %1, off sc0 sc1\n\ts_nop 1" :: "v"(gp_), "v"(v) : "memory"); }
;         float s = 0.f;
; #pragma unroll
;         for (int j = 0; j < 4; ++j) { const float a = __uint_as_float(v[j] << 16), b = __uint_as_float(v[j] & 0xffff0000u); s += a * a + b * b; }
;         s += __shfl_xor(s, 1); s += __shfl_xor(s, 2); s += __shfl_xor(s, 4);
;         if (ch == 0) atomicAdd(ss + (long)row * 4, s); }
;     ...
;     { auto rr = __builtin_amdgcn_permlane32_swap(__float_as_uint(l_reg), __float_as_uint(l_reg), false, false); l_reg = __uint_as_float(rr[0]) + __uint_as_float(rr[1]); }
;     if (hi == 0) wsf[32 + r32] = l_reg; asm volatile("s_waitcnt lgkmcnt(0)" ::: "memory");
;     float rli[16];
; #pragma unroll
;     for (int r = 0; r < 16; ++r) rli[r] = __builtin_amdgcn_rcpf(wsf[32 + crow(r, hi)]);
;     at::store_tile(o, rli, (bf16_t*)(shm + LDS_OST) + wid * 2048, O + (long)(wid * QBLK) * OPITCH, OPITCH, ss + (long)(wid * QBLK) * 4, lane, r32, hi);
.Lgc_full:
	v_mov_b32_e32 v2, v74
	s_nop 1
	v_permlane32_swap_b32_e32 v74, v2
	v_cmp_gt_u32_e32 vcc, 32, v15
	s_and_saveexec_b64 s[12:13], vcc
	v_add_f32_e32 v2, v74, v2
	v_lshl_add_u32 v3, v17, 2, s2
	ds_write_b32 v3, v2 offset:49280
	s_or_b64 exec, exec, s[12:13]
	s_waitcnt lgkmcnt(0)
	v_lshl_add_u32 v10, v186, 4, s2
	ds_read_b128 v[2:5], v10 offset:49280
	ds_read_b128 v[6:9], v10 offset:49312
	s_lshl_b64 s[12:13], s[4:5], 11
	s_add_u32 s10, s10, s12
	s_addc_u32 s11, s11, s13
	s_lshl_b64 s[4:5], s[4:5], 4
	s_add_u32 s8, s8, s4
	s_waitcnt lgkmcnt(1)
	v_rcp_f32_e32 v11, v2
	s_addc_u32 s2, s9, s5
	s_add_u32 s6, s10, s6
	s_addc_u32 s7, s11, s7
	s_lshl_b32 s4, s19, 12
	v_rcp_f32_e32 v12, v3
	v_rcp_f32_e32 v13, v4
	v_rcp_f32_e32 v50, v5
	s_waitcnt lgkmcnt(0)
	v_rcp_f32_e32 v51, v6
	ds_read_b128 v[2:5], v10 offset:49344
	v_rcp_f32_e32 v52, v7
	v_rcp_f32_e32 v53, v8
	v_rcp_f32_e32 v54, v9
	ds_read_b128 v[6:9], v10 offset:49376
	s_add_i32 s9, s4, 0
	v_mul_f32_e32 v10, v18, v11
	v_lshlrev_b32_e32 v0, 1, v0
	v_lshlrev_b32_e32 v17, 1, v17
	v_cvt_pk_bf16_f32 v10, v10, s0
	v_add3_u32 v0, s9, v0, v17
	ds_write_b16 v0, v10 offset:51200
	v_mul_f32_e32 v10, v34, v11
	v_cvt_pk_bf16_f32 v10, v10, s0
	ds_write_b16 v0, v10 offset:51264
	v_mul_f32_e32 v10, v19, v12
	v_cvt_pk_bf16_f32 v10, v10, s0
	ds_write_b16 v0, v10 offset:51328
	v_mul_f32_e32 v10, v35, v12
	v_cvt_pk_bf16_f32 v10, v10, s0
	ds_write_b16 v0, v10 offset:51392
	v_mul_f32_e32 v10, v20, v13
	v_cvt_pk_bf16_f32 v10, v10, s0
	ds_write_b16 v0, v10 offset:51456
	v_mul_f32_e32 v10, v36, v13
	v_cvt_pk_bf16_f32 v10, v10, s0
	ds_write_b16 v0, v10 offset:51520
	v_mul_f32_e32 v10, v21, v50
	v_cvt_pk_bf16_f32 v10, v10, s0
	ds_write_b16 v0, v10 offset:51584
	v_mul_f32_e32 v10, v37, v50
	v_cvt_pk_bf16_f32 v10, v10, s0
	ds_write_b16 v0, v10 offset:51648
	v_mul_f32_e32 v10, v22, v51
	v_cvt_pk_bf16_f32 v10, v10, s0
	ds_write_b16 v0, v10 offset:52224
	v_mul_f32_e32 v10, v38, v51
	v_cvt_pk_bf16_f32 v10, v10, s0
	ds_write_b16 v0, v10 offset:52288
	v_mul_f32_e32 v10, v23, v52
	v_cvt_pk_bf16_f32 v10, v10, s0
	ds_write_b16 v0, v10 offset:52352
	v_mul_f32_e32 v10, v39, v52
	v_cvt_pk_bf16_f32 v10, v10, s0
	ds_write_b16 v0, v10 offset:52416
	v_mul_f32_e32 v10, v24, v53
	v_cvt_pk_bf16_f32 v10, v10, s0
	ds_write_b16 v0, v10 offset:52480
	v_mul_f32_e32 v10, v40, v53
	v_cvt_pk_bf16_f32 v10, v10, s0
	s_waitcnt lgkmcnt(14)
	v_rcp_f32_e32 v2, v2
	ds_write_b16 v0, v10 offset:52544
	v_mul_f32_e32 v10, v25, v54
	v_cvt_pk_bf16_f32 v10, v10, s0
	v_rcp_f32_e32 v3, v3
	ds_write_b16 v0, v10 offset:52608
	v_mul_f32_e32 v10, v41, v54
	v_cvt_pk_bf16_f32 v10, v10, s0
	ds_write_b16 v0, v10 offset:52672
	v_mul_f32_e32 v10, v26, v2
	v_mul_f32_e32 v2, v42, v2
	v_cvt_pk_bf16_f32 v2, v2, s0
	v_rcp_f32_e32 v4, v4
	ds_write_b16 v0, v2 offset:53312
	v_mul_f32_e32 v2, v27, v3
	v_cvt_pk_bf16_f32 v2, v2, s0
	ds_write_b16 v0, v2 offset:53376
	v_mul_f32_e32 v2, v43, v3
	v_cvt_pk_bf16_f32 v2, v2, s0
	v_rcp_f32_e32 v5, v5
	ds_write_b16 v0, v2 offset:53440
	v_mul_f32_e32 v2, v28, v4
	v_cvt_pk_bf16_f32 v2, v2, s0
	ds_write_b16 v0, v2 offset:53504
	v_mul_f32_e32 v2, v44, v4
	v_cvt_pk_bf16_f32 v2, v2, s0
	s_waitcnt lgkmcnt(14)
	v_rcp_f32_e32 v6, v6
	ds_write_b16 v0, v2 offset:53568
	v_mul_f32_e32 v2, v29, v5
	v_cvt_pk_bf16_f32 v2, v2, s0
	ds_write_b16 v0, v2 offset:53632
	v_mul_f32_e32 v2, v45, v5
	v_cvt_pk_bf16_f32 v2, v2, s0
	v_rcp_f32_e32 v7, v7
	ds_write_b16 v0, v2 offset:53696
	v_mul_f32_e32 v2, v30, v6
	v_cvt_pk_bf16_f32 v2, v2, s0
	ds_write_b16 v0, v2 offset:54272
	v_mul_f32_e32 v2, v46, v6
	v_cvt_pk_bf16_f32 v2, v2, s0
	v_rcp_f32_e32 v8, v8
	ds_write_b16 v0, v2 offset:54336
	v_mul_f32_e32 v2, v31, v7
	v_cvt_pk_bf16_f32 v2, v2, s0
	ds_write_b16 v0, v2 offset:54400
	v_mul_f32_e32 v2, v47, v7
	v_cvt_pk_bf16_f32 v2, v2, s0
	v_rcp_f32_e32 v9, v9
	ds_write_b16 v0, v2 offset:54464
	v_mul_f32_e32 v2, v32, v8
	v_cvt_pk_bf16_f32 v2, v2, s0
	ds_write_b16 v0, v2 offset:54528
	v_mul_f32_e32 v2, v48, v8
	v_cvt_pk_bf16_f32 v2, v2, s0
	ds_write_b16 v0, v2 offset:54592
	v_mul_f32_e32 v2, v33, v9
	v_cvt_pk_bf16_f32 v2, v2, s0
	ds_write_b16 v0, v2 offset:54656
	v_mul_f32_e32 v2, v49, v9
	v_cvt_pk_bf16_f32 v10, v10, s0
	v_cvt_pk_bf16_f32 v2, v2, s0
	v_and_b32_e32 v6, 7, v14
	ds_write_b16 v0, v10 offset:53248
	ds_write_b16 v0, v2 offset:54720
	v_lshlrev_b32_e32 v0, 4, v6
	v_lshrrev_b32_e32 v7, 3, v15
	v_add_u32_e32 v8, s9, v0
	s_waitcnt lgkmcnt(0)
	v_lshl_add_u32 v2, v7, 7, v8
	ds_read_b128 v[12:15], v2 offset:51200
	s_lshl_b64 s[4:5], s[0:1], 11
	s_add_u32 s6, s6, s4
	s_addc_u32 s7, s7, s5
	s_lshl_b64 s[0:1], s[0:1], 4
	s_waitcnt lgkmcnt(0)
	v_and_b32_e32 v3, 0xffff0000, v12
	v_lshlrev_b32_e32 v2, 16, v12
	v_mul_f32_e32 v3, v3, v3
	v_and_b32_e32 v4, 0xffff0000, v13
	v_fmac_f32_e32 v3, v2, v2
	v_lshlrev_b32_e32 v2, 16, v13
	v_mul_f32_e32 v4, v4, v4
	v_fmac_f32_e32 v4, v2, v2
	v_add_f32_e32 v2, v3, v4
	v_and_b32_e32 v4, 0xffff0000, v14
	v_lshlrev_b32_e32 v3, 16, v14
	v_mul_f32_e32 v4, v4, v4
	v_fmac_f32_e32 v4, v3, v3
	v_add_f32_e32 v2, v4, v2
	v_and_b32_e32 v4, 0xffff0000, v15
	v_lshlrev_b32_e32 v3, 16, v15
	v_mul_f32_e32 v4, v4, v4
	v_fmac_f32_e32 v4, v3, v3
	v_and_b32_e32 v3, 64, v220
	v_add_f32_e32 v5, v4, v2
	v_xor_b32_e32 v2, 1, v220
	v_add_u32_e32 v10, 64, v3
	v_cmp_lt_i32_e32 vcc, v2, v10
	s_add_u32 s0, s8, s0
	s_addc_u32 s1, s2, s1
	v_cndmask_b32_e32 v2, v220, v2, vcc
	v_lshlrev_b32_e32 v4, 2, v2
	ds_bpermute_b32 v9, v4, v5
	v_lshl_add_u64 v[2:3], s[6:7], 0, v[0:1]
	v_xor_b32_e32 v0, 2, v220
	v_cmp_lt_i32_e32 vcc, v0, v10
	s_add_u32 s4, s0, 0x200008
	s_waitcnt lgkmcnt(0)
	v_add_f32_e32 v9, v5, v9
	v_cndmask_b32_e32 v0, v220, v0, vcc
	v_lshlrev_b32_e32 v5, 2, v0
	s_addc_u32 s5, s1, 0
	ds_bpermute_b32 v11, v5, v9
	s_mov_b64 s[0:1], 0x12e40500
	v_lshl_add_u64 v[2:3], v[2:3], 0, s[0:1]
	v_lshlrev_b32_e32 v0, 11, v7
	v_lshl_add_u64 v[18:19], v[2:3], 0, v[0:1]
	v_xor_b32_e32 v0, 4, v220
	v_cmp_lt_i32_e64 s[0:1], v0, v10
	v_cmp_eq_u32_e32 vcc, 0, v6
	s_waitcnt lgkmcnt(0)
	v_add_f32_e32 v9, v9, v11
	v_cndmask_b32_e64 v0, v220, v0, s[0:1]
	v_lshlrev_b32_e32 v6, 2, v0
	ds_bpermute_b32 v10, v6, v9
	global_store_dwordx4 v[18:19], v[12:15], off sc0 sc1
	s_nop 1
	s_and_saveexec_b64 s[0:1], vcc
	v_readlane_b32 s36, v253, 25
	v_readlane_b32 s37, v253, 26
	v_readlane_b32 s38, v253, 27
	v_readlane_b32 s39, v253, 28
	v_readlane_b32 s40, v253, 29
	v_readlane_b32 s41, v253, 30
	v_readlane_b32 s42, v253, 31
	v_readlane_b32 s43, v253, 32
	v_readlane_b32 s44, v253, 33
	v_readlane_b32 s45, v253, 34
	v_readlane_b32 s46, v253, 35
	v_readlane_b32 s47, v253, 36
	v_readlane_b32 s48, v253, 37
	v_readlane_b32 s49, v253, 38
	v_readlane_b32 s50, v253, 39
	v_readlane_b32 s51, v253, 40
	s_cbranch_execz .LBB0_881
	v_lshlrev_b32_e32 v0, 4, v7
	v_lshl_add_u64 v[12:13], s[4:5], 0, v[0:1]
	s_waitcnt lgkmcnt(0)
	v_add_f32_e32 v0, v9, v10
	flat_atomic_add_f32 v[12:13], v0
